# v60 + GEMM K-loops (SSDIn, BCV, conv-out, FFN1, FFN2): first iteration peeled with inline-0 accumulator input, per-tile accumulator zeroing removed
# baseline (speedup 1.0000x reference)
; #define PG8_STAGE(bufoff, gbase, voff) do { _Pragma("unroll") for (int _i = 0; _i < 2; ++_i) \
;         __builtin_amdgcn_global_load_lds((const unsigned*)((const char*)(gbase) + (voff)[_i]), (LAS unsigned*)(lds + (bufoff) + ldsw + _i * 8192), 16, 0, 0); } while (0)
; #define PG8_LDA(dst, b, h) do { _Pragma("unroll") for (int m = 0; m < 4; ++m) _Pragma("unroll") for (int k = 0; k < 2; ++k) dst[m][k] = *(const LAS bf16x8*)(lds + PG8_SA(b, h) + aoff + m * 2048 + k * 1024); } while (0)
; #define PG8_LDB(dst, b, h) do { _Pragma("unroll") for (int n = 0; n < 2; ++n) _Pragma("unroll") for (int k = 0; k < 2; ++k) dst[n][k] = *(const LAS bf16x8*)(lds + PG8_SB(b, h) + boff + n * 2048 + k * 1024); } while (0)
; #define PG8_MMA(ai, bj, At, Bt) do { __builtin_amdgcn_s_setprio(1); _Pragma("unroll") for (int m = 0; m < 4; ++m) _Pragma("unroll") for (int n = 0; n < 2; ++n) _Pragma("unroll") for (int k = 0; k < 2; ++k) \
;         acc[ai][bj][m][n] = __builtin_amdgcn_mfma_f32_16x16x32_bf16(Bt[n][k], At[m][k], acc[ai][bj][m][n], 0, 0, 0); __builtin_amdgcn_s_setprio(0); } while (0)
; #define PG8_WAIT_V(n) asm volatile("s_waitcnt vmcnt(" #n ")" ::: "memory")
; #define PG8_WAIT_L(n) asm volatile("s_waitcnt lgkmcnt(" #n ")" ::: "memory")
; #define PG8_BAR __builtin_amdgcn_s_barrier()
; #define PG8_SCHED __builtin_amdgcn_sched_barrier(0)
; template <class Epi, bool ALIGN_EPI = PG8_ALIGN, bool SP2 = PG8_SP2>
; __device__ __forceinline__ void gemm_phase(LAS uchar* lds, const Gemm g, const StaticOrder& S, const Epi& E) {
;     ...
;     f32x4 acc[2][2][4][2];
; #pragma unroll
;     for (int a = 0; a < 2; ++a)
; #pragma unroll
;         for (int b = 0; b < 2; ++b)
; #pragma unroll
;             for (int m = 0; m < 4; ++m)
; #pragma unroll
;                 for (int n = 0; n < 2; ++n) acc[a][b][m][n] = (f32x4){0.f, 0.f, 0.f, 0.f};
;     ...
;             PG8_LDB(B0, 0, 0); PG8_LDB(B1, 0, 1); PG8_SCHED; PG8_LDA(At, 0, 0); PG8_STAGE(PG8_SA(1, 1), a1 + hstepA, voffA);
;             PG8_WAIT_V(8); PG8_WAIT_L(0); PG8_BAR; PG8_MMA(0, 0, At, B0); PG8_MMA(0, 1, At, B1); PG8_BAR; PG8_SCHED;
;     ...
;                     for (int n = 0; n < 2; ++n) acc[a][b][m][n] = (f32x4){0.f, 0.f, 0.f, 0.f};
.LBB0_344:
	s_add_u32 s38, s4, 0x100
	s_addc_u32 s39, s5, 0
	s_mov_b32 s40, -2
	s_add_u32 s18, s16, 0x100
	s_addc_u32 s19, s17, 0
	s_add_i32 s41, 0, 0x10000
	s_cmp_eq_u32 s40, 12
	s_cselect_b32 s21, s7, s19
	s_cselect_b32 s20, s6, s18
	v_add_u32_e32 v168, s41, v139
	s_cselect_b32 s5, s15, s39
	s_cselect_b32 s4, s14, s38
	s_add_i32 s42, 0, 0x14000
	ds_read_b128 v[164:167], v168
	ds_read_b128 v[172:175], v168 offset:1024
	ds_read_b128 v[176:179], v168 offset:2048
	ds_read_b128 v[184:187], v168 offset:3072
	v_add_u32_e32 v168, s42, v139
	ds_read_b128 v[188:191], v168
	ds_read_b128 v[192:195], v168 offset:1024
	ds_read_b128 v[196:199], v168 offset:2048
	ds_read_b128 v[200:203], v168 offset:3072
	v_lshl_add_u64 v[168:169], s[16:17], 0, v[160:161]
	s_add_i32 m0, s25, 0xc000
	ds_read_b128 v[204:207], v171
	ds_read_b128 v[208:211], v171 offset:1024
	ds_read_b128 v[212:215], v171 offset:2048
	ds_read_b128 v[216:219], v171 offset:3072
	ds_read_b128 v[220:223], v171 offset:4096
	ds_read_b128 v[224:227], v171 offset:5120
	ds_read_b128 v[228:231], v171 offset:6144
	ds_read_b128 v[232:235], v171 offset:7168
	global_load_lds_dwordx4 v[168:169], off
	v_lshl_add_u64 v[168:169], s[16:17], 0, v[162:163]
	s_add_i32 m0, s25, 0xe000
	s_nop 0
	global_load_lds_dwordx4 v[168:169], off
	s_cmp_lt_i32 s40, 0
	s_cbranch_scc0 .Lrw_std_345_0_pl
	s_cmp_eq_u32 s97, 1
	s_cbranch_scc0 .Lrw_std_345_0_pl
	s_waitcnt vmcnt(24)
	s_branch .Lrw_done_345_0_pl

; #define PG8_STAGE(bufoff, gbase, voff) do { _Pragma("unroll") for (int _i = 0; _i < 2; ++_i) \
;         __builtin_amdgcn_global_load_lds((const unsigned*)((const char*)(gbase) + (voff)[_i]), (LAS unsigned*)(lds + (bufoff) + ldsw + _i * 8192), 16, 0, 0); } while (0)
; #define PG8_LDA(dst, b, h) do { _Pragma("unroll") for (int m = 0; m < 4; ++m) _Pragma("unroll") for (int k = 0; k < 2; ++k) dst[m][k] = *(const LAS bf16x8*)(lds + PG8_SA(b, h) + aoff + m * 2048 + k * 1024); } while (0)
; #define PG8_LDB(dst, b, h) do { _Pragma("unroll") for (int n = 0; n < 2; ++n) _Pragma("unroll") for (int k = 0; k < 2; ++k) dst[n][k] = *(const LAS bf16x8*)(lds + PG8_SB(b, h) + boff + n * 2048 + k * 1024); } while (0)
; #define PG8_MMA(ai, bj, At, Bt) do { __builtin_amdgcn_s_setprio(1); _Pragma("unroll") for (int m = 0; m < 4; ++m) _Pragma("unroll") for (int n = 0; n < 2; ++n) _Pragma("unroll") for (int k = 0; k < 2; ++k) \
;         acc[ai][bj][m][n] = __builtin_amdgcn_mfma_f32_16x16x32_bf16(Bt[n][k], At[m][k], acc[ai][bj][m][n], 0, 0, 0); __builtin_amdgcn_s_setprio(0); } while (0)
; #define PG8_WAIT_V(n) asm volatile("s_waitcnt vmcnt(" #n ")" ::: "memory")
; #define PG8_WAIT_L(n) asm volatile("s_waitcnt lgkmcnt(" #n ")" ::: "memory")
; #define PG8_BAR __builtin_amdgcn_s_barrier()
; #define PG8_SCHED __builtin_amdgcn_sched_barrier(0)
; template <class Epi, bool ALIGN_EPI = PG8_ALIGN, bool SP2 = PG8_SP2>
; __device__ __forceinline__ void gemm_phase(LAS uchar* lds, const Gemm g, const StaticOrder& S, const Epi& E) {
;     ...
;             PG8_LDB(B0, 0, 0); PG8_LDB(B1, 0, 1); PG8_SCHED; PG8_LDA(At, 0, 0); PG8_STAGE(PG8_SA(1, 1), a1 + hstepA, voffA);
;             PG8_WAIT_V(8); PG8_WAIT_L(0); PG8_BAR; PG8_MMA(0, 0, At, B0); PG8_MMA(0, 1, At, B1); PG8_BAR; PG8_SCHED;
;             PG8_LDA(At, 0, 1); PG8_STAGE(PG8_SB(0, 0), b2, voffB); PG8_STAGE(PG8_SB(0, 1), b2 + hstepB, voffB); PG8_STAGE(PG8_SA(0, 0), a2, voffA);
;             PG8_WAIT_V(8); PG8_WAIT_L(0); PG8_BAR; PG8_MMA(1, 0, At, B0); PG8_MMA(1, 1, At, B1); PG8_BAR; PG8_SCHED;
.Lrw_done_345_0_pl:
	s_waitcnt lgkmcnt(0)
	s_barrier
	s_setprio 1
	s_waitcnt lgkmcnt(0)
	v_mfma_f32_16x16x32_bf16 v[126:129], v[164:167], v[204:207], 0
	v_mfma_f32_16x16x32_bf16 v[122:125], v[176:179], v[204:207], 0
	v_mfma_f32_16x16x32_bf16 v[118:121], v[164:167], v[212:215], 0
	v_mfma_f32_16x16x32_bf16 v[110:113], v[176:179], v[212:215], 0
	v_mfma_f32_16x16x32_bf16 v[102:105], v[164:167], v[220:223], 0
	v_mfma_f32_16x16x32_bf16 v[94:97], v[176:179], v[220:223], 0
	v_mfma_f32_16x16x32_bf16 v[86:89], v[164:167], v[228:231], 0
	v_mfma_f32_16x16x32_bf16 v[78:81], v[176:179], v[228:231], 0
	v_mfma_f32_16x16x32_bf16 v[126:129], v[172:175], v[208:211], v[126:129]
	v_mfma_f32_16x16x32_bf16 v[122:125], v[184:187], v[208:211], v[122:125]
	v_mfma_f32_16x16x32_bf16 v[118:121], v[172:175], v[216:219], v[118:121]
	v_mfma_f32_16x16x32_bf16 v[110:113], v[184:187], v[216:219], v[110:113]
	v_mfma_f32_16x16x32_bf16 v[102:105], v[172:175], v[224:227], v[102:105]
	v_mfma_f32_16x16x32_bf16 v[94:97], v[184:187], v[224:227], v[94:97]
	v_mfma_f32_16x16x32_bf16 v[86:89], v[172:175], v[232:235], v[86:89]
	v_mfma_f32_16x16x32_bf16 v[78:81], v[184:187], v[232:235], v[78:81]
	s_setprio 0
	s_setprio 1
	v_mfma_f32_16x16x32_bf16 v[114:117], v[188:191], v[204:207], 0
	v_mfma_f32_16x16x32_bf16 v[106:109], v[196:199], v[204:207], 0
	v_mfma_f32_16x16x32_bf16 v[98:101], v[188:191], v[212:215], 0
	v_mfma_f32_16x16x32_bf16 v[90:93], v[196:199], v[212:215], 0
	v_mfma_f32_16x16x32_bf16 v[82:85], v[188:191], v[220:223], 0
	v_mfma_f32_16x16x32_bf16 v[74:77], v[196:199], v[220:223], 0
	v_mfma_f32_16x16x32_bf16 v[70:73], v[188:191], v[228:231], 0
	v_mfma_f32_16x16x32_bf16 v[66:69], v[196:199], v[228:231], 0
	v_mfma_f32_16x16x32_bf16 v[114:117], v[192:195], v[208:211], v[114:117]
	v_mfma_f32_16x16x32_bf16 v[106:109], v[200:203], v[208:211], v[106:109]
	v_mfma_f32_16x16x32_bf16 v[98:101], v[192:195], v[216:219], v[98:101]
	v_mfma_f32_16x16x32_bf16 v[90:93], v[200:203], v[216:219], v[90:93]
	v_mfma_f32_16x16x32_bf16 v[82:85], v[192:195], v[224:227], v[82:85]
	v_mfma_f32_16x16x32_bf16 v[74:77], v[200:203], v[224:227], v[74:77]
	v_mfma_f32_16x16x32_bf16 v[70:73], v[192:195], v[232:235], v[70:73]
	v_mfma_f32_16x16x32_bf16 v[66:69], v[200:203], v[232:235], v[66:69]
	s_setprio 0
	s_barrier
	s_add_i32 s16, s41, s23
	v_lshl_add_u64 v[168:169], s[4:5], 0, v[134:135]
	s_mov_b32 m0, s16
	ds_read_b128 v[204:207], v171 offset:16384
	ds_read_b128 v[208:211], v171 offset:17408
	ds_read_b128 v[212:215], v171 offset:18432
	ds_read_b128 v[216:219], v171 offset:19456
	ds_read_b128 v[220:223], v171 offset:20480
	ds_read_b128 v[224:227], v171 offset:21504
	ds_read_b128 v[228:231], v171 offset:22528
	ds_read_b128 v[232:235], v171 offset:23552
	global_load_lds_dwordx4 v[168:169], off
	s_add_i32 m0, s16, 0x2000
	s_add_u32 s16, s4, 0x44000
	v_lshl_add_u64 v[180:181], s[4:5], 0, v[130:131]
	s_addc_u32 s17, s5, 0
	s_add_i32 s41, s42, s23
	global_load_lds_dwordx4 v[180:181], off
	v_lshl_add_u64 v[236:237], s[16:17], 0, v[134:135]
	s_mov_b32 m0, s41
	v_lshl_add_u64 v[238:239], s[20:21], 0, v[132:133]
	global_load_lds_dwordx4 v[236:237], off
	v_lshl_add_u64 v[236:237], s[16:17], 0, v[130:131]
	s_add_i32 m0, s41, 0x2000
	s_nop 0
	global_load_lds_dwordx4 v[236:237], off
	v_lshl_add_u64 v[236:237], s[20:21], 0, v[156:157]
	s_mov_b32 m0, s25
	s_nop 0
	global_load_lds_dwordx4 v[236:237], off
	s_mov_b32 m0, s26
	s_nop 0
	global_load_lds_dwordx4 v[238:239], off
	s_cmp_lt_i32 s40, 0
	s_cbranch_scc0 .Lrw_std_345_1_pl
	s_cmp_eq_u32 s97, 1
	s_cbranch_scc0 .Lrw_std_345_1_pl
	s_waitcnt vmcnt(24)
	s_branch .Lrw_done_345_1_pl

; #define PG8_STAGE(bufoff, gbase, voff) do { _Pragma("unroll") for (int _i = 0; _i < 2; ++_i) \
;         __builtin_amdgcn_global_load_lds((const unsigned*)((const char*)(gbase) + (voff)[_i]), (LAS unsigned*)(lds + (bufoff) + ldsw + _i * 8192), 16, 0, 0); } while (0)
; #define PG8_LDA(dst, b, h) do { _Pragma("unroll") for (int m = 0; m < 4; ++m) _Pragma("unroll") for (int k = 0; k < 2; ++k) dst[m][k] = *(const LAS bf16x8*)(lds + PG8_SA(b, h) + aoff + m * 2048 + k * 1024); } while (0)
; #define PG8_LDB(dst, b, h) do { _Pragma("unroll") for (int n = 0; n < 2; ++n) _Pragma("unroll") for (int k = 0; k < 2; ++k) dst[n][k] = *(const LAS bf16x8*)(lds + PG8_SB(b, h) + boff + n * 2048 + k * 1024); } while (0)
; #define PG8_MMA(ai, bj, At, Bt) do { __builtin_amdgcn_s_setprio(1); _Pragma("unroll") for (int m = 0; m < 4; ++m) _Pragma("unroll") for (int n = 0; n < 2; ++n) _Pragma("unroll") for (int k = 0; k < 2; ++k) \
;         acc[ai][bj][m][n] = __builtin_amdgcn_mfma_f32_16x16x32_bf16(Bt[n][k], At[m][k], acc[ai][bj][m][n], 0, 0, 0); __builtin_amdgcn_s_setprio(0); } while (0)
; #define PG8_WAIT_V(n) asm volatile("s_waitcnt vmcnt(" #n ")" ::: "memory")
; #define PG8_WAIT_L(n) asm volatile("s_waitcnt lgkmcnt(" #n ")" ::: "memory")
; #define PG8_BAR __builtin_amdgcn_s_barrier()
; #define PG8_SCHED __builtin_amdgcn_sched_barrier(0)
; template <class Epi, bool ALIGN_EPI = PG8_ALIGN, bool SP2 = PG8_SP2>
; __device__ __forceinline__ void gemm_phase(LAS uchar* lds, const Gemm g, const StaticOrder& S, const Epi& E) {
;     ...
;             PG8_WAIT_V(8); PG8_WAIT_L(0); PG8_BAR; PG8_MMA(1, 0, At, B0); PG8_MMA(1, 1, At, B1); PG8_BAR; PG8_SCHED;
;             PG8_LDB(B0, 1, 0); PG8_LDB(B1, 1, 1); PG8_SCHED; PG8_LDA(At, 1, 0); PG8_STAGE(PG8_SA(0, 1), a2 + hstepA, voffA);
;             PG8_WAIT_V(8); PG8_WAIT_L(0); PG8_BAR; PG8_MMA(0, 0, At, B0); PG8_MMA(0, 1, At, B1); PG8_BAR; PG8_SCHED;
.Lrw_done_345_1_pl:
	s_waitcnt lgkmcnt(0)
	s_barrier
	s_setprio 1
	s_waitcnt lgkmcnt(0)
	v_mfma_f32_16x16x32_bf16 v[62:65], v[164:167], v[204:207], 0
	v_mfma_f32_16x16x32_bf16 v[58:61], v[176:179], v[204:207], 0
	v_mfma_f32_16x16x32_bf16 v[54:57], v[164:167], v[212:215], 0
	v_mfma_f32_16x16x32_bf16 v[46:49], v[176:179], v[212:215], 0
	v_mfma_f32_16x16x32_bf16 v[38:41], v[164:167], v[220:223], 0
	v_mfma_f32_16x16x32_bf16 v[30:33], v[176:179], v[220:223], 0
	v_mfma_f32_16x16x32_bf16 v[22:25], v[164:167], v[228:231], 0
	v_mfma_f32_16x16x32_bf16 v[14:17], v[176:179], v[228:231], 0
	v_mfma_f32_16x16x32_bf16 v[62:65], v[172:175], v[208:211], v[62:65]
	v_mfma_f32_16x16x32_bf16 v[58:61], v[184:187], v[208:211], v[58:61]
	v_mfma_f32_16x16x32_bf16 v[54:57], v[172:175], v[216:219], v[54:57]
	v_mfma_f32_16x16x32_bf16 v[46:49], v[184:187], v[216:219], v[46:49]
	v_mfma_f32_16x16x32_bf16 v[38:41], v[172:175], v[224:227], v[38:41]
	v_mfma_f32_16x16x32_bf16 v[30:33], v[184:187], v[224:227], v[30:33]
	v_mfma_f32_16x16x32_bf16 v[22:25], v[172:175], v[232:235], v[22:25]
	v_mfma_f32_16x16x32_bf16 v[14:17], v[184:187], v[232:235], v[14:17]
	s_setprio 0
	s_setprio 1
	v_mfma_f32_16x16x32_bf16 v[50:53], v[188:191], v[204:207], 0
	v_mfma_f32_16x16x32_bf16 v[42:45], v[196:199], v[204:207], 0
	v_mfma_f32_16x16x32_bf16 v[34:37], v[188:191], v[212:215], 0
	v_mfma_f32_16x16x32_bf16 v[26:29], v[196:199], v[212:215], 0
	v_mfma_f32_16x16x32_bf16 v[18:21], v[188:191], v[220:223], 0
	v_mfma_f32_16x16x32_bf16 v[10:13], v[196:199], v[220:223], 0
	v_mfma_f32_16x16x32_bf16 v[6:9], v[188:191], v[228:231], 0
	v_mfma_f32_16x16x32_bf16 v[2:5], v[196:199], v[228:231], 0
	v_mfma_f32_16x16x32_bf16 v[50:53], v[192:195], v[208:211], v[50:53]
	v_mfma_f32_16x16x32_bf16 v[42:45], v[200:203], v[208:211], v[42:45]
	v_mfma_f32_16x16x32_bf16 v[34:37], v[192:195], v[216:219], v[34:37]
	v_mfma_f32_16x16x32_bf16 v[26:29], v[200:203], v[216:219], v[26:29]
	v_mfma_f32_16x16x32_bf16 v[18:21], v[192:195], v[224:227], v[18:21]
	v_mfma_f32_16x16x32_bf16 v[10:13], v[200:203], v[224:227], v[10:13]
	v_mfma_f32_16x16x32_bf16 v[6:9], v[192:195], v[232:235], v[6:9]
	v_mfma_f32_16x16x32_bf16 v[2:5], v[200:203], v[232:235], v[2:5]
	s_setprio 0
	s_barrier
	s_add_i32 s41, 0, 0x18000
	s_add_i32 s42, 0, 0x1c000
	v_add_u32_e32 v184, s41, v139
	v_add_u32_e32 v200, s42, v139
	ds_read_b128 v[164:167], v184
	ds_read_b128 v[172:175], v184 offset:1024
	ds_read_b128 v[176:179], v184 offset:2048
	ds_read_b128 v[184:187], v184 offset:3072
	ds_read_b128 v[188:191], v200
	ds_read_b128 v[192:195], v200 offset:1024
	ds_read_b128 v[196:199], v200 offset:2048
	ds_read_b128 v[200:203], v200 offset:3072
	s_add_u32 s16, s20, 0x44000
	s_addc_u32 s17, s21, 0
	s_mov_b32 m0, s27
	v_lshl_add_u64 v[240:241], s[16:17], 0, v[156:157]
	ds_read_b128 v[204:207], v171 offset:32768
	ds_read_b128 v[208:211], v171 offset:33792
	ds_read_b128 v[212:215], v171 offset:34816
	ds_read_b128 v[216:219], v171 offset:35840
	ds_read_b128 v[220:223], v171 offset:36864
	ds_read_b128 v[224:227], v171 offset:37888
	ds_read_b128 v[228:231], v171 offset:38912
	ds_read_b128 v[232:235], v171 offset:39936
	global_load_lds_dwordx4 v[240:241], off
	v_lshl_add_u64 v[240:241], s[16:17], 0, v[132:133]
	s_mov_b32 m0, s28
	s_nop 0
	global_load_lds_dwordx4 v[240:241], off
	s_waitcnt vmcnt(8)
	s_waitcnt lgkmcnt(0)
	s_barrier
	s_setprio 1
	s_waitcnt lgkmcnt(0)
	v_mfma_f32_16x16x32_bf16 v[126:129], v[164:167], v[204:207], v[126:129]
	v_mfma_f32_16x16x32_bf16 v[122:125], v[176:179], v[204:207], v[122:125]
	v_mfma_f32_16x16x32_bf16 v[118:121], v[164:167], v[212:215], v[118:121]
	v_mfma_f32_16x16x32_bf16 v[110:113], v[176:179], v[212:215], v[110:113]
	v_mfma_f32_16x16x32_bf16 v[102:105], v[164:167], v[220:223], v[102:105]
	v_mfma_f32_16x16x32_bf16 v[94:97], v[176:179], v[220:223], v[94:97]
	v_mfma_f32_16x16x32_bf16 v[86:89], v[164:167], v[228:231], v[86:89]
	v_mfma_f32_16x16x32_bf16 v[78:81], v[176:179], v[228:231], v[78:81]
	v_mfma_f32_16x16x32_bf16 v[126:129], v[172:175], v[208:211], v[126:129]
	v_mfma_f32_16x16x32_bf16 v[122:125], v[184:187], v[208:211], v[122:125]
	v_mfma_f32_16x16x32_bf16 v[118:121], v[172:175], v[216:219], v[118:121]
	v_mfma_f32_16x16x32_bf16 v[110:113], v[184:187], v[216:219], v[110:113]
	v_mfma_f32_16x16x32_bf16 v[102:105], v[172:175], v[224:227], v[102:105]
	v_mfma_f32_16x16x32_bf16 v[94:97], v[184:187], v[224:227], v[94:97]
	v_mfma_f32_16x16x32_bf16 v[86:89], v[172:175], v[232:235], v[86:89]
	v_mfma_f32_16x16x32_bf16 v[78:81], v[184:187], v[232:235], v[78:81]
	s_setprio 0
	s_setprio 1
	v_mfma_f32_16x16x32_bf16 v[114:117], v[188:191], v[204:207], v[114:117]
	v_mfma_f32_16x16x32_bf16 v[106:109], v[196:199], v[204:207], v[106:109]
	v_mfma_f32_16x16x32_bf16 v[98:101], v[188:191], v[212:215], v[98:101]
	v_mfma_f32_16x16x32_bf16 v[90:93], v[196:199], v[212:215], v[90:93]
	v_mfma_f32_16x16x32_bf16 v[82:85], v[188:191], v[220:223], v[82:85]
	v_mfma_f32_16x16x32_bf16 v[74:77], v[196:199], v[220:223], v[74:77]
	v_mfma_f32_16x16x32_bf16 v[70:73], v[188:191], v[228:231], v[70:73]
	v_mfma_f32_16x16x32_bf16 v[66:69], v[196:199], v[228:231], v[66:69]
	v_mfma_f32_16x16x32_bf16 v[114:117], v[192:195], v[208:211], v[114:117]
	v_mfma_f32_16x16x32_bf16 v[106:109], v[200:203], v[208:211], v[106:109]
	v_mfma_f32_16x16x32_bf16 v[98:101], v[192:195], v[216:219], v[98:101]
	v_mfma_f32_16x16x32_bf16 v[90:93], v[200:203], v[216:219], v[90:93]
	v_mfma_f32_16x16x32_bf16 v[82:85], v[192:195], v[224:227], v[82:85]
	v_mfma_f32_16x16x32_bf16 v[74:77], v[200:203], v[224:227], v[74:77]
	v_mfma_f32_16x16x32_bf16 v[70:73], v[192:195], v[232:235], v[70:73]
	v_mfma_f32_16x16x32_bf16 v[66:69], v[200:203], v[232:235], v[66:69]
	s_setprio 0
	s_barrier
; #define PG8_STAGE(bufoff, gbase, voff) do { _Pragma("unroll") for (int _i = 0; _i < 2; ++_i) \
;         __builtin_amdgcn_global_load_lds((const unsigned*)((const char*)(gbase) + (voff)[_i]), (LAS unsigned*)(lds + (bufoff) + ldsw + _i * 8192), 16, 0, 0); } while (0)
; #define PG8_LDA(dst, b, h) do { _Pragma("unroll") for (int m = 0; m < 4; ++m) _Pragma("unroll") for (int k = 0; k < 2; ++k) dst[m][k] = *(const LAS bf16x8*)(lds + PG8_SA(b, h) + aoff + m * 2048 + k * 1024); } while (0)
; #define PG8_MMA(ai, bj, At, Bt) do { __builtin_amdgcn_s_setprio(1); _Pragma("unroll") for (int m = 0; m < 4; ++m) _Pragma("unroll") for (int n = 0; n < 2; ++n) _Pragma("unroll") for (int k = 0; k < 2; ++k) \
;         acc[ai][bj][m][n] = __builtin_amdgcn_mfma_f32_16x16x32_bf16(Bt[n][k], At[m][k], acc[ai][bj][m][n], 0, 0, 0); __builtin_amdgcn_s_setprio(0); } while (0)
; #define PG8_WAIT_V(n) asm volatile("s_waitcnt vmcnt(" #n ")" ::: "memory")
; #define PG8_WAIT_L(n) asm volatile("s_waitcnt lgkmcnt(" #n ")" ::: "memory")
; #define PG8_BAR __builtin_amdgcn_s_barrier()
; #define PG8_SCHED __builtin_amdgcn_sched_barrier(0)
; template <class Epi, bool ALIGN_EPI = PG8_ALIGN, bool SP2 = PG8_SP2>
; __device__ __forceinline__ void gemm_phase(LAS uchar* lds, const Gemm g, const StaticOrder& S, const Epi& E) {
;     ...
;             PG8_WAIT_V(8); PG8_WAIT_L(0); PG8_BAR; PG8_MMA(0, 0, At, B0); PG8_MMA(0, 1, At, B1); PG8_BAR; PG8_SCHED;
;             PG8_LDA(At, 1, 1); PG8_STAGE(PG8_SB(1, 0), b3, voffB); PG8_STAGE(PG8_SB(1, 1), b3 + hstepB, voffB); PG8_STAGE(PG8_SA(1, 0), a3, voffA);
;             PG8_WAIT_V(8); PG8_WAIT_L(0); PG8_BAR; PG8_MMA(1, 0, At, B0); PG8_MMA(1, 1, At, B1); PG8_BAR; PG8_SCHED;
	s_add_i32 s16, s41, s23
	v_lshl_add_u64 v[168:169], v[168:169], 0, s[84:85]
	s_mov_b32 m0, s16
	ds_read_b128 v[204:207], v171 offset:49152
	ds_read_b128 v[208:211], v171 offset:50176
	ds_read_b128 v[212:215], v171 offset:51200
	ds_read_b128 v[216:219], v171 offset:52224
	ds_read_b128 v[220:223], v171 offset:53248
	ds_read_b128 v[224:227], v171 offset:54272
	ds_read_b128 v[228:231], v171 offset:55296
	ds_read_b128 v[232:235], v171 offset:56320
	global_load_lds_dwordx4 v[168:169], off
	s_add_i32 m0, s16, 0x2000
	s_add_u32 s4, s4, 0x44080
	v_lshl_add_u64 v[168:169], v[180:181], 0, s[84:85]
	s_addc_u32 s5, s5, 0
	s_add_i32 s16, s42, s23
	global_load_lds_dwordx4 v[168:169], off
	v_lshl_add_u64 v[168:169], s[4:5], 0, v[134:135]
	s_mov_b32 m0, s16
	s_nop 0
	global_load_lds_dwordx4 v[168:169], off
	v_lshl_add_u64 v[168:169], s[4:5], 0, v[130:131]
	s_add_i32 m0, s16, 0x2000
	s_nop 0
	global_load_lds_dwordx4 v[168:169], off
	v_lshl_add_u64 v[168:169], v[236:237], 0, s[84:85]
	s_mov_b32 m0, s29
	s_nop 0
	global_load_lds_dwordx4 v[168:169], off
	v_lshl_add_u64 v[168:169], v[238:239], 0, s[84:85]
	s_mov_b32 m0, s30
	s_nop 0
	global_load_lds_dwordx4 v[168:169], off
	s_waitcnt vmcnt(8)
	s_waitcnt lgkmcnt(0)
	s_barrier
	s_setprio 1
	s_waitcnt lgkmcnt(0)
	v_mfma_f32_16x16x32_bf16 v[62:65], v[164:167], v[204:207], v[62:65]
	v_mfma_f32_16x16x32_bf16 v[58:61], v[176:179], v[204:207], v[58:61]
	v_mfma_f32_16x16x32_bf16 v[54:57], v[164:167], v[212:215], v[54:57]
	v_mfma_f32_16x16x32_bf16 v[46:49], v[176:179], v[212:215], v[46:49]
	v_mfma_f32_16x16x32_bf16 v[38:41], v[164:167], v[220:223], v[38:41]
	v_mfma_f32_16x16x32_bf16 v[30:33], v[176:179], v[220:223], v[30:33]
	v_mfma_f32_16x16x32_bf16 v[22:25], v[164:167], v[228:231], v[22:25]
	v_mfma_f32_16x16x32_bf16 v[14:17], v[176:179], v[228:231], v[14:17]
	v_mfma_f32_16x16x32_bf16 v[62:65], v[172:175], v[208:211], v[62:65]
	v_mfma_f32_16x16x32_bf16 v[58:61], v[184:187], v[208:211], v[58:61]
	v_mfma_f32_16x16x32_bf16 v[54:57], v[172:175], v[216:219], v[54:57]
	v_mfma_f32_16x16x32_bf16 v[46:49], v[184:187], v[216:219], v[46:49]
	v_mfma_f32_16x16x32_bf16 v[38:41], v[172:175], v[224:227], v[38:41]
	v_mfma_f32_16x16x32_bf16 v[30:33], v[184:187], v[224:227], v[30:33]
	v_mfma_f32_16x16x32_bf16 v[22:25], v[172:175], v[232:235], v[22:25]
	v_mfma_f32_16x16x32_bf16 v[14:17], v[184:187], v[232:235], v[14:17]
	s_setprio 0
	s_setprio 1
	v_mfma_f32_16x16x32_bf16 v[50:53], v[188:191], v[204:207], v[50:53]
	v_mfma_f32_16x16x32_bf16 v[42:45], v[196:199], v[204:207], v[42:45]
	v_mfma_f32_16x16x32_bf16 v[34:37], v[188:191], v[212:215], v[34:37]
	v_mfma_f32_16x16x32_bf16 v[26:29], v[196:199], v[212:215], v[26:29]
	v_mfma_f32_16x16x32_bf16 v[18:21], v[188:191], v[220:223], v[18:21]
	v_mfma_f32_16x16x32_bf16 v[10:13], v[196:199], v[220:223], v[10:13]
	v_mfma_f32_16x16x32_bf16 v[6:9], v[188:191], v[228:231], v[6:9]
	v_mfma_f32_16x16x32_bf16 v[2:5], v[196:199], v[228:231], v[2:5]
	v_mfma_f32_16x16x32_bf16 v[50:53], v[192:195], v[208:211], v[50:53]
	v_mfma_f32_16x16x32_bf16 v[42:45], v[200:203], v[208:211], v[42:45]
	v_mfma_f32_16x16x32_bf16 v[34:37], v[192:195], v[216:219], v[34:37]
	v_mfma_f32_16x16x32_bf16 v[26:29], v[200:203], v[216:219], v[26:29]
	v_mfma_f32_16x16x32_bf16 v[18:21], v[192:195], v[224:227], v[18:21]
	v_mfma_f32_16x16x32_bf16 v[10:13], v[200:203], v[224:227], v[10:13]
	v_mfma_f32_16x16x32_bf16 v[6:9], v[192:195], v[232:235], v[6:9]
	v_mfma_f32_16x16x32_bf16 v[2:5], v[200:203], v[232:235], v[2:5]
	s_setprio 0
	s_barrier
	s_add_i32 s40, s40, 2
	s_add_u32 s38, s38, 0x100
	s_addc_u32 s39, s39, 0
	s_cmp_gt_u32 s40, 13
	s_mov_b64 s[16:17], s[18:19]

; #define PG8_STAGE(bufoff, gbase, voff) do { _Pragma("unroll") for (int _i = 0; _i < 2; ++_i) \
;         __builtin_amdgcn_global_load_lds((const unsigned*)((const char*)(gbase) + (voff)[_i]), (LAS unsigned*)(lds + (bufoff) + ldsw + _i * 8192), 16, 0, 0); } while (0)
; #define PG8_LDA(dst, b, h) do { _Pragma("unroll") for (int m = 0; m < 4; ++m) _Pragma("unroll") for (int k = 0; k < 2; ++k) dst[m][k] = *(const LAS bf16x8*)(lds + PG8_SA(b, h) + aoff + m * 2048 + k * 1024); } while (0)
; #define PG8_LDB(dst, b, h) do { _Pragma("unroll") for (int n = 0; n < 2; ++n) _Pragma("unroll") for (int k = 0; k < 2; ++k) dst[n][k] = *(const LAS bf16x8*)(lds + PG8_SB(b, h) + boff + n * 2048 + k * 1024); } while (0)
; #define PG8_MMA(ai, bj, At, Bt) do { __builtin_amdgcn_s_setprio(1); _Pragma("unroll") for (int m = 0; m < 4; ++m) _Pragma("unroll") for (int n = 0; n < 2; ++n) _Pragma("unroll") for (int k = 0; k < 2; ++k) \
;         acc[ai][bj][m][n] = __builtin_amdgcn_mfma_f32_16x16x32_bf16(Bt[n][k], At[m][k], acc[ai][bj][m][n], 0, 0, 0); __builtin_amdgcn_s_setprio(0); } while (0)
; #define PG8_WAIT_V(n) asm volatile("s_waitcnt vmcnt(" #n ")" ::: "memory")
; #define PG8_WAIT_L(n) asm volatile("s_waitcnt lgkmcnt(" #n ")" ::: "memory")
; #define PG8_BAR __builtin_amdgcn_s_barrier()
; #define PG8_SCHED __builtin_amdgcn_sched_barrier(0)
; template <class Epi, bool ALIGN_EPI = PG8_ALIGN, bool SP2 = PG8_SP2>
; __device__ __forceinline__ void gemm_phase(LAS uchar* lds, const Gemm g, const StaticOrder& S, const Epi& E) {
;     ...
;             const bool last = (t == nt - 2);
;             const char* a1 = cA + (size_t)(t + 1) * kstep;
;             const char* a2 = last ? nA : cA + (size_t)(t + 2) * kstep; const char* b2 = last ? nB : cB + (size_t)(t + 2) * kstep;
;             const char* a3 = a2 + kstep; const char* b3 = b2 + kstep;
;             if constexpr (SP2) {
;             PG8_LDB(B0, 0, 0); PG8_LDB(B1, 0, 1); PG8_SCHED; PG8_LDA(At, 0, 0); PG8_STAGE(PG8_SA(1, 1), a1 + hstepA, voffA);
;             PG8_WAIT_V(8); PG8_WAIT_L(0); PG8_BAR; PG8_MMA(0, 0, At, B0); PG8_MMA(0, 1, At, B1); PG8_BAR; PG8_SCHED;
;             PG8_LDA(At, 0, 1); PG8_STAGE(PG8_SB(0, 0), b2, voffB); PG8_STAGE(PG8_SB(0, 1), b2 + hstepB, voffB); PG8_STAGE(PG8_SA(0, 0), a2, voffA);
;             PG8_WAIT_V(8); PG8_WAIT_L(0); PG8_BAR; PG8_MMA(1, 0, At, B0); PG8_MMA(1, 1, At, B1); PG8_BAR; PG8_SCHED;
.LBB0_668:
	s_add_u32 s36, s14, 0x100
	s_addc_u32 s37, s15, 0
	s_mov_b32 s38, -2
	s_add_u32 s14, s12, 0x100
	s_addc_u32 s15, s13, 0
	s_add_i32 s39, 0, 0x10000
	s_cmp_eq_u32 s38, 12
	s_cselect_b32 s19, s5, s15
	s_cselect_b32 s18, s4, s14
	s_cselect_b32 s17, s11, s37
	s_cselect_b32 s16, s10, s36
	s_add_i32 s40, 0, 0x14000
	v_add_u32_e32 v174, s39, v139
	v_add_u32_e32 v192, s40, v139
	ds_read_b128 v[160:163], v174
	ds_read_b128 v[164:167], v174 offset:1024
	ds_read_b128 v[168:171], v174 offset:2048
	ds_read_b128 v[174:177], v174 offset:3072
	ds_read_b128 v[178:181], v192
	ds_read_b128 v[184:187], v192 offset:1024
	ds_read_b128 v[188:191], v192 offset:2048
	ds_read_b128 v[192:195], v192 offset:3072
	v_lshl_add_u64 v[228:229], s[12:13], 0, v[156:157]
	s_add_i32 m0, s23, 0xc000
	ds_read_b128 v[196:199], v173
	ds_read_b128 v[200:203], v173 offset:1024
	ds_read_b128 v[204:207], v173 offset:2048
	ds_read_b128 v[208:211], v173 offset:3072
	ds_read_b128 v[212:215], v173 offset:4096
	ds_read_b128 v[216:219], v173 offset:5120
	ds_read_b128 v[220:223], v173 offset:6144
	ds_read_b128 v[224:227], v173 offset:7168
	global_load_lds_dwordx4 v[228:229], off
	v_lshl_add_u64 v[228:229], s[12:13], 0, v[158:159]
	s_add_i32 m0, s23, 0xe000
	s_nop 0
	global_load_lds_dwordx4 v[228:229], off
	s_waitcnt vmcnt(8)
	s_waitcnt lgkmcnt(0)
	s_barrier
	s_setprio 1
	s_waitcnt lgkmcnt(0)
	v_mfma_f32_16x16x32_bf16 v[126:129], v[160:163], v[196:199], 0
	v_mfma_f32_16x16x32_bf16 v[122:125], v[168:171], v[196:199], 0
	v_mfma_f32_16x16x32_bf16 v[118:121], v[160:163], v[204:207], 0
	v_mfma_f32_16x16x32_bf16 v[110:113], v[168:171], v[204:207], 0
	v_mfma_f32_16x16x32_bf16 v[102:105], v[160:163], v[212:215], 0
	v_mfma_f32_16x16x32_bf16 v[94:97], v[168:171], v[212:215], 0
	v_mfma_f32_16x16x32_bf16 v[86:89], v[160:163], v[220:223], 0
	v_mfma_f32_16x16x32_bf16 v[78:81], v[168:171], v[220:223], 0
	v_mfma_f32_16x16x32_bf16 v[126:129], v[164:167], v[200:203], v[126:129]
	v_mfma_f32_16x16x32_bf16 v[122:125], v[174:177], v[200:203], v[122:125]
	v_mfma_f32_16x16x32_bf16 v[118:121], v[164:167], v[208:211], v[118:121]
	v_mfma_f32_16x16x32_bf16 v[110:113], v[174:177], v[208:211], v[110:113]
	v_mfma_f32_16x16x32_bf16 v[102:105], v[164:167], v[216:219], v[102:105]
	v_mfma_f32_16x16x32_bf16 v[94:97], v[174:177], v[216:219], v[94:97]
	v_mfma_f32_16x16x32_bf16 v[86:89], v[164:167], v[224:227], v[86:89]
	v_mfma_f32_16x16x32_bf16 v[78:81], v[174:177], v[224:227], v[78:81]
	s_setprio 0
	s_setprio 1
	v_mfma_f32_16x16x32_bf16 v[114:117], v[178:181], v[196:199], 0
	v_mfma_f32_16x16x32_bf16 v[106:109], v[188:191], v[196:199], 0
	v_mfma_f32_16x16x32_bf16 v[98:101], v[178:181], v[204:207], 0
	v_mfma_f32_16x16x32_bf16 v[90:93], v[188:191], v[204:207], 0
	v_mfma_f32_16x16x32_bf16 v[82:85], v[178:181], v[212:215], 0
	v_mfma_f32_16x16x32_bf16 v[74:77], v[188:191], v[212:215], 0
	v_mfma_f32_16x16x32_bf16 v[70:73], v[178:181], v[220:223], 0
	v_mfma_f32_16x16x32_bf16 v[66:69], v[188:191], v[220:223], 0
	v_mfma_f32_16x16x32_bf16 v[114:117], v[184:187], v[200:203], v[114:117]
	v_mfma_f32_16x16x32_bf16 v[106:109], v[192:195], v[200:203], v[106:109]
	v_mfma_f32_16x16x32_bf16 v[98:101], v[184:187], v[208:211], v[98:101]
	v_mfma_f32_16x16x32_bf16 v[90:93], v[192:195], v[208:211], v[90:93]
	v_mfma_f32_16x16x32_bf16 v[82:85], v[184:187], v[216:219], v[82:85]
	v_mfma_f32_16x16x32_bf16 v[74:77], v[192:195], v[216:219], v[74:77]
	v_mfma_f32_16x16x32_bf16 v[70:73], v[184:187], v[224:227], v[70:73]
	v_mfma_f32_16x16x32_bf16 v[66:69], v[192:195], v[224:227], v[66:69]
	s_setprio 0
	s_barrier
	s_add_i32 s12, s39, s21
	v_lshl_add_u64 v[228:229], s[16:17], 0, v[134:135]
	s_mov_b32 m0, s12
	ds_read_b128 v[196:199], v173 offset:16384
	ds_read_b128 v[200:203], v173 offset:17408
	ds_read_b128 v[204:207], v173 offset:18432
	ds_read_b128 v[208:211], v173 offset:19456
	ds_read_b128 v[212:215], v173 offset:20480
	ds_read_b128 v[216:219], v173 offset:21504
	ds_read_b128 v[220:223], v173 offset:22528
	ds_read_b128 v[224:227], v173 offset:23552
	global_load_lds_dwordx4 v[228:229], off
	s_add_i32 m0, s12, 0x2000
	s_add_u32 s12, s16, 0x44000
	v_lshl_add_u64 v[230:231], s[16:17], 0, v[130:131]
	s_addc_u32 s13, s17, 0
	s_add_i32 s39, s40, s21
	global_load_lds_dwordx4 v[230:231], off
	v_lshl_add_u64 v[232:233], s[12:13], 0, v[134:135]
	s_mov_b32 m0, s39
	v_lshl_add_u64 v[234:235], s[18:19], 0, v[132:133]
	global_load_lds_dwordx4 v[232:233], off
	v_lshl_add_u64 v[232:233], s[12:13], 0, v[130:131]
	s_add_i32 m0, s39, 0x2000
	s_nop 0
	global_load_lds_dwordx4 v[232:233], off
	v_lshl_add_u64 v[232:233], s[18:19], 0, v[152:153]
	s_mov_b32 m0, s23
	s_nop 0
	global_load_lds_dwordx4 v[232:233], off
	s_mov_b32 m0, s24
	s_nop 0
	global_load_lds_dwordx4 v[234:235], off
	s_waitcnt vmcnt(8)
	s_waitcnt lgkmcnt(0)
	s_barrier
; #define PG8_STAGE(bufoff, gbase, voff) do { _Pragma("unroll") for (int _i = 0; _i < 2; ++_i) \
;         __builtin_amdgcn_global_load_lds((const unsigned*)((const char*)(gbase) + (voff)[_i]), (LAS unsigned*)(lds + (bufoff) + ldsw + _i * 8192), 16, 0, 0); } while (0)
; #define PG8_LDA(dst, b, h) do { _Pragma("unroll") for (int m = 0; m < 4; ++m) _Pragma("unroll") for (int k = 0; k < 2; ++k) dst[m][k] = *(const LAS bf16x8*)(lds + PG8_SA(b, h) + aoff + m * 2048 + k * 1024); } while (0)
; #define PG8_LDB(dst, b, h) do { _Pragma("unroll") for (int n = 0; n < 2; ++n) _Pragma("unroll") for (int k = 0; k < 2; ++k) dst[n][k] = *(const LAS bf16x8*)(lds + PG8_SB(b, h) + boff + n * 2048 + k * 1024); } while (0)
; #define PG8_MMA(ai, bj, At, Bt) do { __builtin_amdgcn_s_setprio(1); _Pragma("unroll") for (int m = 0; m < 4; ++m) _Pragma("unroll") for (int n = 0; n < 2; ++n) _Pragma("unroll") for (int k = 0; k < 2; ++k) \
;         acc[ai][bj][m][n] = __builtin_amdgcn_mfma_f32_16x16x32_bf16(Bt[n][k], At[m][k], acc[ai][bj][m][n], 0, 0, 0); __builtin_amdgcn_s_setprio(0); } while (0)
; #define PG8_WAIT_V(n) asm volatile("s_waitcnt vmcnt(" #n ")" ::: "memory")
; #define PG8_WAIT_L(n) asm volatile("s_waitcnt lgkmcnt(" #n ")" ::: "memory")
; #define PG8_BAR __builtin_amdgcn_s_barrier()
; #define PG8_SCHED __builtin_amdgcn_sched_barrier(0)
; template <class Epi, bool ALIGN_EPI = PG8_ALIGN, bool SP2 = PG8_SP2>
; __device__ __forceinline__ void gemm_phase(LAS uchar* lds, const Gemm g, const StaticOrder& S, const Epi& E) {
;     ...
;             PG8_WAIT_V(8); PG8_WAIT_L(0); PG8_BAR; PG8_MMA(1, 0, At, B0); PG8_MMA(1, 1, At, B1); PG8_BAR; PG8_SCHED;
;             PG8_LDB(B0, 1, 0); PG8_LDB(B1, 1, 1); PG8_SCHED; PG8_LDA(At, 1, 0); PG8_STAGE(PG8_SA(0, 1), a2 + hstepA, voffA);
;             PG8_WAIT_V(8); PG8_WAIT_L(0); PG8_BAR; PG8_MMA(0, 0, At, B0); PG8_MMA(0, 1, At, B1); PG8_BAR; PG8_SCHED;
	s_setprio 1
	s_waitcnt lgkmcnt(0)
	v_mfma_f32_16x16x32_bf16 v[62:65], v[160:163], v[196:199], 0
	v_mfma_f32_16x16x32_bf16 v[58:61], v[168:171], v[196:199], 0
	v_mfma_f32_16x16x32_bf16 v[54:57], v[160:163], v[204:207], 0
	v_mfma_f32_16x16x32_bf16 v[46:49], v[168:171], v[204:207], 0
	v_mfma_f32_16x16x32_bf16 v[38:41], v[160:163], v[212:215], 0
	v_mfma_f32_16x16x32_bf16 v[30:33], v[168:171], v[212:215], 0
	v_mfma_f32_16x16x32_bf16 v[22:25], v[160:163], v[220:223], 0
	v_mfma_f32_16x16x32_bf16 v[14:17], v[168:171], v[220:223], 0
	v_mfma_f32_16x16x32_bf16 v[62:65], v[164:167], v[200:203], v[62:65]
	v_mfma_f32_16x16x32_bf16 v[58:61], v[174:177], v[200:203], v[58:61]
	v_mfma_f32_16x16x32_bf16 v[54:57], v[164:167], v[208:211], v[54:57]
	v_mfma_f32_16x16x32_bf16 v[46:49], v[174:177], v[208:211], v[46:49]
	v_mfma_f32_16x16x32_bf16 v[38:41], v[164:167], v[216:219], v[38:41]
	v_mfma_f32_16x16x32_bf16 v[30:33], v[174:177], v[216:219], v[30:33]
	v_mfma_f32_16x16x32_bf16 v[22:25], v[164:167], v[224:227], v[22:25]
	v_mfma_f32_16x16x32_bf16 v[14:17], v[174:177], v[224:227], v[14:17]
	s_setprio 0
	s_setprio 1
	v_mfma_f32_16x16x32_bf16 v[50:53], v[178:181], v[196:199], 0
	v_mfma_f32_16x16x32_bf16 v[42:45], v[188:191], v[196:199], 0
	v_mfma_f32_16x16x32_bf16 v[34:37], v[178:181], v[204:207], 0
	v_mfma_f32_16x16x32_bf16 v[26:29], v[188:191], v[204:207], 0
	v_mfma_f32_16x16x32_bf16 v[18:21], v[178:181], v[212:215], 0
	v_mfma_f32_16x16x32_bf16 v[10:13], v[188:191], v[212:215], 0
	v_mfma_f32_16x16x32_bf16 v[6:9], v[178:181], v[220:223], 0
	v_mfma_f32_16x16x32_bf16 v[2:5], v[188:191], v[220:223], 0
	v_mfma_f32_16x16x32_bf16 v[50:53], v[184:187], v[200:203], v[50:53]
	v_mfma_f32_16x16x32_bf16 v[42:45], v[192:195], v[200:203], v[42:45]
	v_mfma_f32_16x16x32_bf16 v[34:37], v[184:187], v[208:211], v[34:37]
	v_mfma_f32_16x16x32_bf16 v[26:29], v[192:195], v[208:211], v[26:29]
	v_mfma_f32_16x16x32_bf16 v[18:21], v[184:187], v[216:219], v[18:21]
	v_mfma_f32_16x16x32_bf16 v[10:13], v[192:195], v[216:219], v[10:13]
	v_mfma_f32_16x16x32_bf16 v[6:9], v[184:187], v[224:227], v[6:9]
	v_mfma_f32_16x16x32_bf16 v[2:5], v[192:195], v[224:227], v[2:5]
	s_setprio 0
	s_barrier
	s_add_i32 s39, 0, 0x18000
	s_add_i32 s40, 0, 0x1c000
	v_add_u32_e32 v174, s39, v139
	v_add_u32_e32 v192, s40, v139
	ds_read_b128 v[160:163], v174
	ds_read_b128 v[164:167], v174 offset:1024
	ds_read_b128 v[168:171], v174 offset:2048
	ds_read_b128 v[174:177], v174 offset:3072
	ds_read_b128 v[178:181], v192
	ds_read_b128 v[184:187], v192 offset:1024
	ds_read_b128 v[188:191], v192 offset:2048
	ds_read_b128 v[192:195], v192 offset:3072
	s_add_u32 s12, s18, 0x44000
	s_addc_u32 s13, s19, 0
	s_mov_b32 m0, s25
	v_lshl_add_u64 v[236:237], s[12:13], 0, v[152:153]
	ds_read_b128 v[196:199], v173 offset:32768
	ds_read_b128 v[200:203], v173 offset:33792
	ds_read_b128 v[204:207], v173 offset:34816
	ds_read_b128 v[208:211], v173 offset:35840
	ds_read_b128 v[212:215], v173 offset:36864
	ds_read_b128 v[216:219], v173 offset:37888
	ds_read_b128 v[220:223], v173 offset:38912
	ds_read_b128 v[224:227], v173 offset:39936
	global_load_lds_dwordx4 v[236:237], off
	v_lshl_add_u64 v[236:237], s[12:13], 0, v[132:133]
	s_mov_b32 m0, s26
	s_nop 0
	global_load_lds_dwordx4 v[236:237], off
	s_waitcnt vmcnt(8)
	s_waitcnt lgkmcnt(0)
	s_barrier
	s_setprio 1
	s_waitcnt lgkmcnt(0)
	v_mfma_f32_16x16x32_bf16 v[126:129], v[160:163], v[196:199], v[126:129]
	v_mfma_f32_16x16x32_bf16 v[122:125], v[168:171], v[196:199], v[122:125]
	v_mfma_f32_16x16x32_bf16 v[118:121], v[160:163], v[204:207], v[118:121]
	v_mfma_f32_16x16x32_bf16 v[110:113], v[168:171], v[204:207], v[110:113]
	v_mfma_f32_16x16x32_bf16 v[102:105], v[160:163], v[212:215], v[102:105]
	v_mfma_f32_16x16x32_bf16 v[94:97], v[168:171], v[212:215], v[94:97]
	v_mfma_f32_16x16x32_bf16 v[86:89], v[160:163], v[220:223], v[86:89]
	v_mfma_f32_16x16x32_bf16 v[78:81], v[168:171], v[220:223], v[78:81]
	v_mfma_f32_16x16x32_bf16 v[126:129], v[164:167], v[200:203], v[126:129]
	v_mfma_f32_16x16x32_bf16 v[122:125], v[174:177], v[200:203], v[122:125]
	v_mfma_f32_16x16x32_bf16 v[118:121], v[164:167], v[208:211], v[118:121]
	v_mfma_f32_16x16x32_bf16 v[110:113], v[174:177], v[208:211], v[110:113]
	v_mfma_f32_16x16x32_bf16 v[102:105], v[164:167], v[216:219], v[102:105]
	v_mfma_f32_16x16x32_bf16 v[94:97], v[174:177], v[216:219], v[94:97]
	v_mfma_f32_16x16x32_bf16 v[86:89], v[164:167], v[224:227], v[86:89]
	v_mfma_f32_16x16x32_bf16 v[78:81], v[174:177], v[224:227], v[78:81]
	s_setprio 0
	s_setprio 1
	v_mfma_f32_16x16x32_bf16 v[114:117], v[178:181], v[196:199], v[114:117]
	v_mfma_f32_16x16x32_bf16 v[106:109], v[188:191], v[196:199], v[106:109]
	v_mfma_f32_16x16x32_bf16 v[98:101], v[178:181], v[204:207], v[98:101]
	v_mfma_f32_16x16x32_bf16 v[90:93], v[188:191], v[204:207], v[90:93]
	v_mfma_f32_16x16x32_bf16 v[82:85], v[178:181], v[212:215], v[82:85]
	v_mfma_f32_16x16x32_bf16 v[74:77], v[188:191], v[212:215], v[74:77]
	v_mfma_f32_16x16x32_bf16 v[70:73], v[178:181], v[220:223], v[70:73]
	v_mfma_f32_16x16x32_bf16 v[66:69], v[188:191], v[220:223], v[66:69]
	v_mfma_f32_16x16x32_bf16 v[114:117], v[184:187], v[200:203], v[114:117]
	v_mfma_f32_16x16x32_bf16 v[106:109], v[192:195], v[200:203], v[106:109]
	v_mfma_f32_16x16x32_bf16 v[98:101], v[184:187], v[208:211], v[98:101]
	v_mfma_f32_16x16x32_bf16 v[90:93], v[192:195], v[208:211], v[90:93]
	v_mfma_f32_16x16x32_bf16 v[82:85], v[184:187], v[216:219], v[82:85]
	v_mfma_f32_16x16x32_bf16 v[74:77], v[192:195], v[216:219], v[74:77]
	v_mfma_f32_16x16x32_bf16 v[70:73], v[184:187], v[224:227], v[70:73]
	v_mfma_f32_16x16x32_bf16 v[66:69], v[192:195], v[224:227], v[66:69]
	s_setprio 0
	s_barrier
; #define PG8_STAGE(bufoff, gbase, voff) do { _Pragma("unroll") for (int _i = 0; _i < 2; ++_i) \
;         __builtin_amdgcn_global_load_lds((const unsigned*)((const char*)(gbase) + (voff)[_i]), (LAS unsigned*)(lds + (bufoff) + ldsw + _i * 8192), 16, 0, 0); } while (0)
; #define PG8_LDA(dst, b, h) do { _Pragma("unroll") for (int m = 0; m < 4; ++m) _Pragma("unroll") for (int k = 0; k < 2; ++k) dst[m][k] = *(const LAS bf16x8*)(lds + PG8_SA(b, h) + aoff + m * 2048 + k * 1024); } while (0)
; #define PG8_MMA(ai, bj, At, Bt) do { __builtin_amdgcn_s_setprio(1); _Pragma("unroll") for (int m = 0; m < 4; ++m) _Pragma("unroll") for (int n = 0; n < 2; ++n) _Pragma("unroll") for (int k = 0; k < 2; ++k) \
;         acc[ai][bj][m][n] = __builtin_amdgcn_mfma_f32_16x16x32_bf16(Bt[n][k], At[m][k], acc[ai][bj][m][n], 0, 0, 0); __builtin_amdgcn_s_setprio(0); } while (0)
; #define PG8_WAIT_V(n) asm volatile("s_waitcnt vmcnt(" #n ")" ::: "memory")
; #define PG8_WAIT_L(n) asm volatile("s_waitcnt lgkmcnt(" #n ")" ::: "memory")
; #define PG8_BAR __builtin_amdgcn_s_barrier()
; #define PG8_SCHED __builtin_amdgcn_sched_barrier(0)
; template <class Epi, bool ALIGN_EPI = PG8_ALIGN, bool SP2 = PG8_SP2>
; __device__ __forceinline__ void gemm_phase(LAS uchar* lds, const Gemm g, const StaticOrder& S, const Epi& E) {
;     ...
;             PG8_WAIT_V(8); PG8_WAIT_L(0); PG8_BAR; PG8_MMA(0, 0, At, B0); PG8_MMA(0, 1, At, B1); PG8_BAR; PG8_SCHED;
;             PG8_LDA(At, 1, 1); PG8_STAGE(PG8_SB(1, 0), b3, voffB); PG8_STAGE(PG8_SB(1, 1), b3 + hstepB, voffB); PG8_STAGE(PG8_SA(1, 0), a3, voffA);
;             PG8_WAIT_V(8); PG8_WAIT_L(0); PG8_BAR; PG8_MMA(1, 0, At, B0); PG8_MMA(1, 1, At, B1); PG8_BAR; PG8_SCHED;
	s_add_i32 s12, s39, s21
	v_lshl_add_u64 v[228:229], v[228:229], 0, s[84:85]
	s_mov_b32 m0, s12
	ds_read_b128 v[196:199], v173 offset:49152
	ds_read_b128 v[200:203], v173 offset:50176
	ds_read_b128 v[204:207], v173 offset:51200
	ds_read_b128 v[208:211], v173 offset:52224
	ds_read_b128 v[212:215], v173 offset:53248
	ds_read_b128 v[216:219], v173 offset:54272
	ds_read_b128 v[220:223], v173 offset:55296
	ds_read_b128 v[224:227], v173 offset:56320
	global_load_lds_dwordx4 v[228:229], off
	s_add_i32 m0, s12, 0x2000
	s_add_u32 s12, s16, 0x44080
	v_lshl_add_u64 v[228:229], v[230:231], 0, s[84:85]
	s_addc_u32 s13, s17, 0
	s_add_i32 s16, s40, s21
	global_load_lds_dwordx4 v[228:229], off
	v_lshl_add_u64 v[228:229], s[12:13], 0, v[134:135]
	s_mov_b32 m0, s16
	s_nop 0
	global_load_lds_dwordx4 v[228:229], off
	v_lshl_add_u64 v[228:229], s[12:13], 0, v[130:131]
	s_add_i32 m0, s16, 0x2000
	s_nop 0
	global_load_lds_dwordx4 v[228:229], off
	v_lshl_add_u64 v[228:229], v[232:233], 0, s[84:85]
	s_mov_b32 m0, s27
	s_nop 0
	global_load_lds_dwordx4 v[228:229], off
	v_lshl_add_u64 v[228:229], v[234:235], 0, s[84:85]
	s_mov_b32 m0, s28
	s_nop 0
	global_load_lds_dwordx4 v[228:229], off
	s_waitcnt vmcnt(8)
	s_waitcnt lgkmcnt(0)
	s_barrier
	s_setprio 1
	s_waitcnt lgkmcnt(0)
	v_mfma_f32_16x16x32_bf16 v[62:65], v[160:163], v[196:199], v[62:65]
	v_mfma_f32_16x16x32_bf16 v[58:61], v[168:171], v[196:199], v[58:61]
	v_mfma_f32_16x16x32_bf16 v[54:57], v[160:163], v[204:207], v[54:57]
	v_mfma_f32_16x16x32_bf16 v[46:49], v[168:171], v[204:207], v[46:49]
	v_mfma_f32_16x16x32_bf16 v[38:41], v[160:163], v[212:215], v[38:41]
	v_mfma_f32_16x16x32_bf16 v[30:33], v[168:171], v[212:215], v[30:33]
	v_mfma_f32_16x16x32_bf16 v[22:25], v[160:163], v[220:223], v[22:25]
	v_mfma_f32_16x16x32_bf16 v[14:17], v[168:171], v[220:223], v[14:17]
	v_mfma_f32_16x16x32_bf16 v[62:65], v[164:167], v[200:203], v[62:65]
	v_mfma_f32_16x16x32_bf16 v[58:61], v[174:177], v[200:203], v[58:61]
	v_mfma_f32_16x16x32_bf16 v[54:57], v[164:167], v[208:211], v[54:57]
	v_mfma_f32_16x16x32_bf16 v[46:49], v[174:177], v[208:211], v[46:49]
	v_mfma_f32_16x16x32_bf16 v[38:41], v[164:167], v[216:219], v[38:41]
	v_mfma_f32_16x16x32_bf16 v[30:33], v[174:177], v[216:219], v[30:33]
	v_mfma_f32_16x16x32_bf16 v[22:25], v[164:167], v[224:227], v[22:25]
	v_mfma_f32_16x16x32_bf16 v[14:17], v[174:177], v[224:227], v[14:17]
	s_setprio 0
	s_setprio 1
	v_mfma_f32_16x16x32_bf16 v[50:53], v[178:181], v[196:199], v[50:53]
	v_mfma_f32_16x16x32_bf16 v[42:45], v[188:191], v[196:199], v[42:45]
	v_mfma_f32_16x16x32_bf16 v[34:37], v[178:181], v[204:207], v[34:37]
	v_mfma_f32_16x16x32_bf16 v[26:29], v[188:191], v[204:207], v[26:29]
	v_mfma_f32_16x16x32_bf16 v[18:21], v[178:181], v[212:215], v[18:21]
	v_mfma_f32_16x16x32_bf16 v[10:13], v[188:191], v[212:215], v[10:13]
	v_mfma_f32_16x16x32_bf16 v[6:9], v[178:181], v[220:223], v[6:9]
	v_mfma_f32_16x16x32_bf16 v[2:5], v[188:191], v[220:223], v[2:5]
	v_mfma_f32_16x16x32_bf16 v[50:53], v[184:187], v[200:203], v[50:53]
	v_mfma_f32_16x16x32_bf16 v[42:45], v[192:195], v[200:203], v[42:45]
	v_mfma_f32_16x16x32_bf16 v[34:37], v[184:187], v[208:211], v[34:37]
	v_mfma_f32_16x16x32_bf16 v[26:29], v[192:195], v[208:211], v[26:29]
	v_mfma_f32_16x16x32_bf16 v[18:21], v[184:187], v[216:219], v[18:21]
	v_mfma_f32_16x16x32_bf16 v[10:13], v[192:195], v[216:219], v[10:13]
	v_mfma_f32_16x16x32_bf16 v[6:9], v[184:187], v[224:227], v[6:9]
	v_mfma_f32_16x16x32_bf16 v[2:5], v[192:195], v[224:227], v[2:5]
	s_setprio 0
	s_barrier
	s_add_i32 s38, s38, 2
	s_add_u32 s36, s36, 0x100
	s_addc_u32 s37, s37, 0
	s_cmp_gt_u32 s38, 13
	s_mov_b64 s[12:13], s[14:15]

; #define PG8_STAGE(bufoff, gbase, voff) do { _Pragma("unroll") for (int _i = 0; _i < 2; ++_i) \
;         __builtin_amdgcn_global_load_lds((const unsigned*)((const char*)(gbase) + (voff)[_i]), (LAS unsigned*)(lds + (bufoff) + ldsw + _i * 8192), 16, 0, 0); } while (0)
; #define PG8_LDA(dst, b, h) do { _Pragma("unroll") for (int m = 0; m < 4; ++m) _Pragma("unroll") for (int k = 0; k < 2; ++k) dst[m][k] = *(const LAS bf16x8*)(lds + PG8_SA(b, h) + aoff + m * 2048 + k * 1024); } while (0)
; #define PG8_LDB(dst, b, h) do { _Pragma("unroll") for (int n = 0; n < 2; ++n) _Pragma("unroll") for (int k = 0; k < 2; ++k) dst[n][k] = *(const LAS bf16x8*)(lds + PG8_SB(b, h) + boff + n * 2048 + k * 1024); } while (0)
; #define PG8_MMA(ai, bj, At, Bt) do { __builtin_amdgcn_s_setprio(1); _Pragma("unroll") for (int m = 0; m < 4; ++m) _Pragma("unroll") for (int n = 0; n < 2; ++n) _Pragma("unroll") for (int k = 0; k < 2; ++k) \
;         acc[ai][bj][m][n] = __builtin_amdgcn_mfma_f32_16x16x32_bf16(Bt[n][k], At[m][k], acc[ai][bj][m][n], 0, 0, 0); __builtin_amdgcn_s_setprio(0); } while (0)
; #define PG8_WAIT_V(n) asm volatile("s_waitcnt vmcnt(" #n ")" ::: "memory")
; #define PG8_WAIT_L(n) asm volatile("s_waitcnt lgkmcnt(" #n ")" ::: "memory")
; #define PG8_BAR __builtin_amdgcn_s_barrier()
; #define PG8_SCHED __builtin_amdgcn_sched_barrier(0)
; template <class Epi, bool ALIGN_EPI = PG8_ALIGN, bool SP2 = PG8_SP2>
; __device__ __forceinline__ void gemm_phase(LAS uchar* lds, const Gemm g, const StaticOrder& S, const Epi& E) {
;     ...
;             const bool last = (t == nt - 2);
;             const char* a1 = cA + (size_t)(t + 1) * kstep;
;             const char* a2 = last ? nA : cA + (size_t)(t + 2) * kstep; const char* b2 = last ? nB : cB + (size_t)(t + 2) * kstep;
;             const char* a3 = a2 + kstep; const char* b3 = b2 + kstep;
;             if constexpr (SP2) {
;             PG8_LDB(B0, 0, 0); PG8_LDB(B1, 0, 1); PG8_SCHED; PG8_LDA(At, 0, 0); PG8_STAGE(PG8_SA(1, 1), a1 + hstepA, voffA);
;             PG8_WAIT_V(8); PG8_WAIT_L(0); PG8_BAR; PG8_MMA(0, 0, At, B0); PG8_MMA(0, 1, At, B1); PG8_BAR; PG8_SCHED;
;             PG8_LDA(At, 0, 1); PG8_STAGE(PG8_SB(0, 0), b2, voffB); PG8_STAGE(PG8_SB(0, 1), b2 + hstepB, voffB); PG8_STAGE(PG8_SA(0, 0), a2, voffA);
;             PG8_WAIT_V(8); PG8_WAIT_L(0); PG8_BAR; PG8_MMA(1, 0, At, B0); PG8_MMA(1, 1, At, B1); PG8_BAR; PG8_SCHED;
.LBB0_836:
	s_add_u32 s36, s14, 0x100
	s_addc_u32 s37, s15, 0
	s_mov_b32 s38, -2
	s_add_u32 s14, s12, 0x100
	s_addc_u32 s15, s13, 0
	s_add_i32 s39, 0, 0x10000
	s_cmp_eq_u32 s38, 12
	s_cselect_b32 s19, s5, s15
	s_cselect_b32 s18, s4, s14
	s_cselect_b32 s17, s11, s37
	s_cselect_b32 s16, s10, s36
	s_add_i32 s40, 0, 0x14000
	v_add_u32_e32 v174, s39, v139
	v_add_u32_e32 v192, s40, v139
	ds_read_b128 v[160:163], v174
	ds_read_b128 v[166:169], v174 offset:1024
	ds_read_b128 v[170:173], v174 offset:2048
	ds_read_b128 v[174:177], v174 offset:3072
	ds_read_b128 v[178:181], v192
	ds_read_b128 v[184:187], v192 offset:1024
	ds_read_b128 v[188:191], v192 offset:2048
	ds_read_b128 v[192:195], v192 offset:3072
	v_lshl_add_u64 v[228:229], s[12:13], 0, v[156:157]
	s_add_i32 m0, s23, 0xc000
	ds_read_b128 v[196:199], v165
	ds_read_b128 v[200:203], v165 offset:1024
	ds_read_b128 v[204:207], v165 offset:2048
	ds_read_b128 v[208:211], v165 offset:3072
	ds_read_b128 v[212:215], v165 offset:4096
	ds_read_b128 v[216:219], v165 offset:5120
	ds_read_b128 v[220:223], v165 offset:6144
	ds_read_b128 v[224:227], v165 offset:7168
	global_load_lds_dwordx4 v[228:229], off
	v_lshl_add_u64 v[228:229], s[12:13], 0, v[158:159]
	s_add_i32 m0, s23, 0xe000
	s_nop 0
	global_load_lds_dwordx4 v[228:229], off
	s_waitcnt vmcnt(8)
	s_waitcnt lgkmcnt(0)
	s_barrier
	s_setprio 1
	s_waitcnt lgkmcnt(0)
	v_mfma_f32_16x16x32_bf16 v[126:129], v[160:163], v[196:199], 0
	v_mfma_f32_16x16x32_bf16 v[122:125], v[170:173], v[196:199], 0
	v_mfma_f32_16x16x32_bf16 v[118:121], v[160:163], v[204:207], 0
	v_mfma_f32_16x16x32_bf16 v[110:113], v[170:173], v[204:207], 0
	v_mfma_f32_16x16x32_bf16 v[102:105], v[160:163], v[212:215], 0
	v_mfma_f32_16x16x32_bf16 v[94:97], v[170:173], v[212:215], 0
	v_mfma_f32_16x16x32_bf16 v[86:89], v[160:163], v[220:223], 0
	v_mfma_f32_16x16x32_bf16 v[78:81], v[170:173], v[220:223], 0
	v_mfma_f32_16x16x32_bf16 v[126:129], v[166:169], v[200:203], v[126:129]
	v_mfma_f32_16x16x32_bf16 v[122:125], v[174:177], v[200:203], v[122:125]
	v_mfma_f32_16x16x32_bf16 v[118:121], v[166:169], v[208:211], v[118:121]
	v_mfma_f32_16x16x32_bf16 v[110:113], v[174:177], v[208:211], v[110:113]
	v_mfma_f32_16x16x32_bf16 v[102:105], v[166:169], v[216:219], v[102:105]
	v_mfma_f32_16x16x32_bf16 v[94:97], v[174:177], v[216:219], v[94:97]
	v_mfma_f32_16x16x32_bf16 v[86:89], v[166:169], v[224:227], v[86:89]
	v_mfma_f32_16x16x32_bf16 v[78:81], v[174:177], v[224:227], v[78:81]
	s_setprio 0
	s_setprio 1
	v_mfma_f32_16x16x32_bf16 v[114:117], v[178:181], v[196:199], 0
	v_mfma_f32_16x16x32_bf16 v[106:109], v[188:191], v[196:199], 0
	v_mfma_f32_16x16x32_bf16 v[98:101], v[178:181], v[204:207], 0
	v_mfma_f32_16x16x32_bf16 v[90:93], v[188:191], v[204:207], 0
	v_mfma_f32_16x16x32_bf16 v[82:85], v[178:181], v[212:215], 0
	v_mfma_f32_16x16x32_bf16 v[74:77], v[188:191], v[212:215], 0
	v_mfma_f32_16x16x32_bf16 v[70:73], v[178:181], v[220:223], 0
	v_mfma_f32_16x16x32_bf16 v[66:69], v[188:191], v[220:223], 0
	v_mfma_f32_16x16x32_bf16 v[114:117], v[184:187], v[200:203], v[114:117]
	v_mfma_f32_16x16x32_bf16 v[106:109], v[192:195], v[200:203], v[106:109]
	v_mfma_f32_16x16x32_bf16 v[98:101], v[184:187], v[208:211], v[98:101]
	v_mfma_f32_16x16x32_bf16 v[90:93], v[192:195], v[208:211], v[90:93]
	v_mfma_f32_16x16x32_bf16 v[82:85], v[184:187], v[216:219], v[82:85]
	v_mfma_f32_16x16x32_bf16 v[74:77], v[192:195], v[216:219], v[74:77]
	v_mfma_f32_16x16x32_bf16 v[70:73], v[184:187], v[224:227], v[70:73]
	v_mfma_f32_16x16x32_bf16 v[66:69], v[192:195], v[224:227], v[66:69]
	s_setprio 0
	s_barrier
	s_add_i32 s12, s39, s22
	v_lshl_add_u64 v[228:229], s[16:17], 0, v[132:133]
	s_mov_b32 m0, s12
	ds_read_b128 v[196:199], v165 offset:16384
	ds_read_b128 v[200:203], v165 offset:17408
	ds_read_b128 v[204:207], v165 offset:18432
	ds_read_b128 v[208:211], v165 offset:19456
	ds_read_b128 v[212:215], v165 offset:20480
	ds_read_b128 v[216:219], v165 offset:21504
	ds_read_b128 v[220:223], v165 offset:22528
	ds_read_b128 v[224:227], v165 offset:23552
	global_load_lds_dwordx4 v[228:229], off
	s_add_i32 m0, s12, 0x2000
	s_add_u32 s12, s16, 0x44000
	v_lshl_add_u64 v[230:231], s[16:17], 0, v[152:153]
	s_addc_u32 s13, s17, 0
	s_add_i32 s39, s40, s22
	global_load_lds_dwordx4 v[230:231], off
	v_lshl_add_u64 v[232:233], s[12:13], 0, v[132:133]
	s_mov_b32 m0, s39
	v_lshl_add_u64 v[234:235], s[18:19], 0, v[134:135]
	global_load_lds_dwordx4 v[232:233], off
	v_lshl_add_u64 v[232:233], s[12:13], 0, v[152:153]
	s_add_i32 m0, s39, 0x2000
	s_nop 0
	global_load_lds_dwordx4 v[232:233], off
	v_lshl_add_u64 v[232:233], s[18:19], 0, v[130:131]
	s_mov_b32 m0, s23
	s_nop 0
	global_load_lds_dwordx4 v[232:233], off
	s_mov_b32 m0, s24
	s_nop 0
	global_load_lds_dwordx4 v[234:235], off
	s_waitcnt vmcnt(8)
	s_waitcnt lgkmcnt(0)
	s_barrier
; #define PG8_STAGE(bufoff, gbase, voff) do { _Pragma("unroll") for (int _i = 0; _i < 2; ++_i) \
;         __builtin_amdgcn_global_load_lds((const unsigned*)((const char*)(gbase) + (voff)[_i]), (LAS unsigned*)(lds + (bufoff) + ldsw + _i * 8192), 16, 0, 0); } while (0)
; #define PG8_LDA(dst, b, h) do { _Pragma("unroll") for (int m = 0; m < 4; ++m) _Pragma("unroll") for (int k = 0; k < 2; ++k) dst[m][k] = *(const LAS bf16x8*)(lds + PG8_SA(b, h) + aoff + m * 2048 + k * 1024); } while (0)
; #define PG8_LDB(dst, b, h) do { _Pragma("unroll") for (int n = 0; n < 2; ++n) _Pragma("unroll") for (int k = 0; k < 2; ++k) dst[n][k] = *(const LAS bf16x8*)(lds + PG8_SB(b, h) + boff + n * 2048 + k * 1024); } while (0)
; #define PG8_MMA(ai, bj, At, Bt) do { __builtin_amdgcn_s_setprio(1); _Pragma("unroll") for (int m = 0; m < 4; ++m) _Pragma("unroll") for (int n = 0; n < 2; ++n) _Pragma("unroll") for (int k = 0; k < 2; ++k) \
;         acc[ai][bj][m][n] = __builtin_amdgcn_mfma_f32_16x16x32_bf16(Bt[n][k], At[m][k], acc[ai][bj][m][n], 0, 0, 0); __builtin_amdgcn_s_setprio(0); } while (0)
; #define PG8_WAIT_V(n) asm volatile("s_waitcnt vmcnt(" #n ")" ::: "memory")
; #define PG8_WAIT_L(n) asm volatile("s_waitcnt lgkmcnt(" #n ")" ::: "memory")
; #define PG8_BAR __builtin_amdgcn_s_barrier()
; #define PG8_SCHED __builtin_amdgcn_sched_barrier(0)
; template <class Epi, bool ALIGN_EPI = PG8_ALIGN, bool SP2 = PG8_SP2>
; __device__ __forceinline__ void gemm_phase(LAS uchar* lds, const Gemm g, const StaticOrder& S, const Epi& E) {
;     ...
;             PG8_WAIT_V(8); PG8_WAIT_L(0); PG8_BAR; PG8_MMA(1, 0, At, B0); PG8_MMA(1, 1, At, B1); PG8_BAR; PG8_SCHED;
;             PG8_LDB(B0, 1, 0); PG8_LDB(B1, 1, 1); PG8_SCHED; PG8_LDA(At, 1, 0); PG8_STAGE(PG8_SA(0, 1), a2 + hstepA, voffA);
;             PG8_WAIT_V(8); PG8_WAIT_L(0); PG8_BAR; PG8_MMA(0, 0, At, B0); PG8_MMA(0, 1, At, B1); PG8_BAR; PG8_SCHED;
	s_setprio 1
	s_waitcnt lgkmcnt(0)
	v_mfma_f32_16x16x32_bf16 v[62:65], v[160:163], v[196:199], 0
	v_mfma_f32_16x16x32_bf16 v[58:61], v[170:173], v[196:199], 0
	v_mfma_f32_16x16x32_bf16 v[54:57], v[160:163], v[204:207], 0
	v_mfma_f32_16x16x32_bf16 v[46:49], v[170:173], v[204:207], 0
	v_mfma_f32_16x16x32_bf16 v[38:41], v[160:163], v[212:215], 0
	v_mfma_f32_16x16x32_bf16 v[30:33], v[170:173], v[212:215], 0
	v_mfma_f32_16x16x32_bf16 v[22:25], v[160:163], v[220:223], 0
	v_mfma_f32_16x16x32_bf16 v[14:17], v[170:173], v[220:223], 0
	v_mfma_f32_16x16x32_bf16 v[62:65], v[166:169], v[200:203], v[62:65]
	v_mfma_f32_16x16x32_bf16 v[58:61], v[174:177], v[200:203], v[58:61]
	v_mfma_f32_16x16x32_bf16 v[54:57], v[166:169], v[208:211], v[54:57]
	v_mfma_f32_16x16x32_bf16 v[46:49], v[174:177], v[208:211], v[46:49]
	v_mfma_f32_16x16x32_bf16 v[38:41], v[166:169], v[216:219], v[38:41]
	v_mfma_f32_16x16x32_bf16 v[30:33], v[174:177], v[216:219], v[30:33]
	v_mfma_f32_16x16x32_bf16 v[22:25], v[166:169], v[224:227], v[22:25]
	v_mfma_f32_16x16x32_bf16 v[14:17], v[174:177], v[224:227], v[14:17]
	s_setprio 0
	s_setprio 1
	v_mfma_f32_16x16x32_bf16 v[50:53], v[178:181], v[196:199], 0
	v_mfma_f32_16x16x32_bf16 v[42:45], v[188:191], v[196:199], 0
	v_mfma_f32_16x16x32_bf16 v[34:37], v[178:181], v[204:207], 0
	v_mfma_f32_16x16x32_bf16 v[26:29], v[188:191], v[204:207], 0
	v_mfma_f32_16x16x32_bf16 v[18:21], v[178:181], v[212:215], 0
	v_mfma_f32_16x16x32_bf16 v[10:13], v[188:191], v[212:215], 0
	v_mfma_f32_16x16x32_bf16 v[6:9], v[178:181], v[220:223], 0
	v_mfma_f32_16x16x32_bf16 v[2:5], v[188:191], v[220:223], 0
	v_mfma_f32_16x16x32_bf16 v[50:53], v[184:187], v[200:203], v[50:53]
	v_mfma_f32_16x16x32_bf16 v[42:45], v[192:195], v[200:203], v[42:45]
	v_mfma_f32_16x16x32_bf16 v[34:37], v[184:187], v[208:211], v[34:37]
	v_mfma_f32_16x16x32_bf16 v[26:29], v[192:195], v[208:211], v[26:29]
	v_mfma_f32_16x16x32_bf16 v[18:21], v[184:187], v[216:219], v[18:21]
	v_mfma_f32_16x16x32_bf16 v[10:13], v[192:195], v[216:219], v[10:13]
	v_mfma_f32_16x16x32_bf16 v[6:9], v[184:187], v[224:227], v[6:9]
	v_mfma_f32_16x16x32_bf16 v[2:5], v[192:195], v[224:227], v[2:5]
	s_setprio 0
	s_barrier
	s_add_i32 s39, 0, 0x18000
	s_add_i32 s40, 0, 0x1c000
	v_add_u32_e32 v174, s39, v139
	v_add_u32_e32 v192, s40, v139
	ds_read_b128 v[160:163], v174
	ds_read_b128 v[166:169], v174 offset:1024
	ds_read_b128 v[170:173], v174 offset:2048
	ds_read_b128 v[174:177], v174 offset:3072
	ds_read_b128 v[178:181], v192
	ds_read_b128 v[184:187], v192 offset:1024
	ds_read_b128 v[188:191], v192 offset:2048
	ds_read_b128 v[192:195], v192 offset:3072
	s_add_u32 s12, s18, 0x44000
	s_addc_u32 s13, s19, 0
	s_mov_b32 m0, s25
	v_lshl_add_u64 v[236:237], s[12:13], 0, v[130:131]
	ds_read_b128 v[196:199], v165 offset:32768
	ds_read_b128 v[200:203], v165 offset:33792
	ds_read_b128 v[204:207], v165 offset:34816
	ds_read_b128 v[208:211], v165 offset:35840
	ds_read_b128 v[212:215], v165 offset:36864
	ds_read_b128 v[216:219], v165 offset:37888
	ds_read_b128 v[220:223], v165 offset:38912
	ds_read_b128 v[224:227], v165 offset:39936
	global_load_lds_dwordx4 v[236:237], off
	v_lshl_add_u64 v[236:237], s[12:13], 0, v[134:135]
	s_mov_b32 m0, s26
	s_nop 0
	global_load_lds_dwordx4 v[236:237], off
	s_waitcnt vmcnt(8)
	s_waitcnt lgkmcnt(0)
	s_barrier
	s_setprio 1
	s_waitcnt lgkmcnt(0)
	v_mfma_f32_16x16x32_bf16 v[126:129], v[160:163], v[196:199], v[126:129]
	v_mfma_f32_16x16x32_bf16 v[122:125], v[170:173], v[196:199], v[122:125]
	v_mfma_f32_16x16x32_bf16 v[118:121], v[160:163], v[204:207], v[118:121]
	v_mfma_f32_16x16x32_bf16 v[110:113], v[170:173], v[204:207], v[110:113]
	v_mfma_f32_16x16x32_bf16 v[102:105], v[160:163], v[212:215], v[102:105]
	v_mfma_f32_16x16x32_bf16 v[94:97], v[170:173], v[212:215], v[94:97]
	v_mfma_f32_16x16x32_bf16 v[86:89], v[160:163], v[220:223], v[86:89]
	v_mfma_f32_16x16x32_bf16 v[78:81], v[170:173], v[220:223], v[78:81]
	v_mfma_f32_16x16x32_bf16 v[126:129], v[166:169], v[200:203], v[126:129]
	v_mfma_f32_16x16x32_bf16 v[122:125], v[174:177], v[200:203], v[122:125]
	v_mfma_f32_16x16x32_bf16 v[118:121], v[166:169], v[208:211], v[118:121]
	v_mfma_f32_16x16x32_bf16 v[110:113], v[174:177], v[208:211], v[110:113]
	v_mfma_f32_16x16x32_bf16 v[102:105], v[166:169], v[216:219], v[102:105]
	v_mfma_f32_16x16x32_bf16 v[94:97], v[174:177], v[216:219], v[94:97]
	v_mfma_f32_16x16x32_bf16 v[86:89], v[166:169], v[224:227], v[86:89]
	v_mfma_f32_16x16x32_bf16 v[78:81], v[174:177], v[224:227], v[78:81]
	s_setprio 0
	s_setprio 1
	v_mfma_f32_16x16x32_bf16 v[114:117], v[178:181], v[196:199], v[114:117]
	v_mfma_f32_16x16x32_bf16 v[106:109], v[188:191], v[196:199], v[106:109]
	v_mfma_f32_16x16x32_bf16 v[98:101], v[178:181], v[204:207], v[98:101]
	v_mfma_f32_16x16x32_bf16 v[90:93], v[188:191], v[204:207], v[90:93]
	v_mfma_f32_16x16x32_bf16 v[82:85], v[178:181], v[212:215], v[82:85]
	v_mfma_f32_16x16x32_bf16 v[74:77], v[188:191], v[212:215], v[74:77]
	v_mfma_f32_16x16x32_bf16 v[70:73], v[178:181], v[220:223], v[70:73]
	v_mfma_f32_16x16x32_bf16 v[66:69], v[188:191], v[220:223], v[66:69]
	v_mfma_f32_16x16x32_bf16 v[114:117], v[184:187], v[200:203], v[114:117]
	v_mfma_f32_16x16x32_bf16 v[106:109], v[192:195], v[200:203], v[106:109]
	v_mfma_f32_16x16x32_bf16 v[98:101], v[184:187], v[208:211], v[98:101]
	v_mfma_f32_16x16x32_bf16 v[90:93], v[192:195], v[208:211], v[90:93]
	v_mfma_f32_16x16x32_bf16 v[82:85], v[184:187], v[216:219], v[82:85]
	v_mfma_f32_16x16x32_bf16 v[74:77], v[192:195], v[216:219], v[74:77]
	v_mfma_f32_16x16x32_bf16 v[70:73], v[184:187], v[224:227], v[70:73]
	v_mfma_f32_16x16x32_bf16 v[66:69], v[192:195], v[224:227], v[66:69]
	s_setprio 0
	s_barrier
; #define PG8_STAGE(bufoff, gbase, voff) do { _Pragma("unroll") for (int _i = 0; _i < 2; ++_i) \
;         __builtin_amdgcn_global_load_lds((const unsigned*)((const char*)(gbase) + (voff)[_i]), (LAS unsigned*)(lds + (bufoff) + ldsw + _i * 8192), 16, 0, 0); } while (0)
; #define PG8_LDA(dst, b, h) do { _Pragma("unroll") for (int m = 0; m < 4; ++m) _Pragma("unroll") for (int k = 0; k < 2; ++k) dst[m][k] = *(const LAS bf16x8*)(lds + PG8_SA(b, h) + aoff + m * 2048 + k * 1024); } while (0)
; #define PG8_MMA(ai, bj, At, Bt) do { __builtin_amdgcn_s_setprio(1); _Pragma("unroll") for (int m = 0; m < 4; ++m) _Pragma("unroll") for (int n = 0; n < 2; ++n) _Pragma("unroll") for (int k = 0; k < 2; ++k) \
;         acc[ai][bj][m][n] = __builtin_amdgcn_mfma_f32_16x16x32_bf16(Bt[n][k], At[m][k], acc[ai][bj][m][n], 0, 0, 0); __builtin_amdgcn_s_setprio(0); } while (0)
; #define PG8_WAIT_V(n) asm volatile("s_waitcnt vmcnt(" #n ")" ::: "memory")
; #define PG8_WAIT_L(n) asm volatile("s_waitcnt lgkmcnt(" #n ")" ::: "memory")
; #define PG8_BAR __builtin_amdgcn_s_barrier()
; #define PG8_SCHED __builtin_amdgcn_sched_barrier(0)
; template <class Epi, bool ALIGN_EPI = PG8_ALIGN, bool SP2 = PG8_SP2>
; __device__ __forceinline__ void gemm_phase(LAS uchar* lds, const Gemm g, const StaticOrder& S, const Epi& E) {
;     ...
;             PG8_WAIT_V(8); PG8_WAIT_L(0); PG8_BAR; PG8_MMA(0, 0, At, B0); PG8_MMA(0, 1, At, B1); PG8_BAR; PG8_SCHED;
;             PG8_LDA(At, 1, 1); PG8_STAGE(PG8_SB(1, 0), b3, voffB); PG8_STAGE(PG8_SB(1, 1), b3 + hstepB, voffB); PG8_STAGE(PG8_SA(1, 0), a3, voffA);
;             PG8_WAIT_V(8); PG8_WAIT_L(0); PG8_BAR; PG8_MMA(1, 0, At, B0); PG8_MMA(1, 1, At, B1); PG8_BAR; PG8_SCHED;
	s_add_i32 s12, s39, s22
	v_lshl_add_u64 v[228:229], v[228:229], 0, s[84:85]
	s_mov_b32 m0, s12
	ds_read_b128 v[196:199], v165 offset:49152
	ds_read_b128 v[200:203], v165 offset:50176
	ds_read_b128 v[204:207], v165 offset:51200
	ds_read_b128 v[208:211], v165 offset:52224
	ds_read_b128 v[212:215], v165 offset:53248
	ds_read_b128 v[216:219], v165 offset:54272
	ds_read_b128 v[220:223], v165 offset:55296
	ds_read_b128 v[224:227], v165 offset:56320
	global_load_lds_dwordx4 v[228:229], off
	s_add_i32 m0, s12, 0x2000
	s_add_u32 s12, s16, 0x44080
	v_lshl_add_u64 v[228:229], v[230:231], 0, s[84:85]
	s_addc_u32 s13, s17, 0
	s_add_i32 s16, s40, s22
	global_load_lds_dwordx4 v[228:229], off
	v_lshl_add_u64 v[228:229], s[12:13], 0, v[132:133]
	s_mov_b32 m0, s16
	s_nop 0
	global_load_lds_dwordx4 v[228:229], off
	v_lshl_add_u64 v[228:229], s[12:13], 0, v[152:153]
	s_add_i32 m0, s16, 0x2000
	s_nop 0
	global_load_lds_dwordx4 v[228:229], off
	v_lshl_add_u64 v[228:229], v[232:233], 0, s[84:85]
	s_mov_b32 m0, s27
	s_nop 0
	global_load_lds_dwordx4 v[228:229], off
	v_lshl_add_u64 v[228:229], v[234:235], 0, s[84:85]
	s_mov_b32 m0, s28
	s_nop 0
	global_load_lds_dwordx4 v[228:229], off
	s_waitcnt vmcnt(8)
	s_waitcnt lgkmcnt(0)
	s_barrier
	s_setprio 1
	s_waitcnt lgkmcnt(0)
	v_mfma_f32_16x16x32_bf16 v[62:65], v[160:163], v[196:199], v[62:65]
	v_mfma_f32_16x16x32_bf16 v[58:61], v[170:173], v[196:199], v[58:61]
	v_mfma_f32_16x16x32_bf16 v[54:57], v[160:163], v[204:207], v[54:57]
	v_mfma_f32_16x16x32_bf16 v[46:49], v[170:173], v[204:207], v[46:49]
	v_mfma_f32_16x16x32_bf16 v[38:41], v[160:163], v[212:215], v[38:41]
	v_mfma_f32_16x16x32_bf16 v[30:33], v[170:173], v[212:215], v[30:33]
	v_mfma_f32_16x16x32_bf16 v[22:25], v[160:163], v[220:223], v[22:25]
	v_mfma_f32_16x16x32_bf16 v[14:17], v[170:173], v[220:223], v[14:17]
	v_mfma_f32_16x16x32_bf16 v[62:65], v[166:169], v[200:203], v[62:65]
	v_mfma_f32_16x16x32_bf16 v[58:61], v[174:177], v[200:203], v[58:61]
	v_mfma_f32_16x16x32_bf16 v[54:57], v[166:169], v[208:211], v[54:57]
	v_mfma_f32_16x16x32_bf16 v[46:49], v[174:177], v[208:211], v[46:49]
	v_mfma_f32_16x16x32_bf16 v[38:41], v[166:169], v[216:219], v[38:41]
	v_mfma_f32_16x16x32_bf16 v[30:33], v[174:177], v[216:219], v[30:33]
	v_mfma_f32_16x16x32_bf16 v[22:25], v[166:169], v[224:227], v[22:25]
	v_mfma_f32_16x16x32_bf16 v[14:17], v[174:177], v[224:227], v[14:17]
	s_setprio 0
	s_setprio 1
	v_mfma_f32_16x16x32_bf16 v[50:53], v[178:181], v[196:199], v[50:53]
	v_mfma_f32_16x16x32_bf16 v[42:45], v[188:191], v[196:199], v[42:45]
	v_mfma_f32_16x16x32_bf16 v[34:37], v[178:181], v[204:207], v[34:37]
	v_mfma_f32_16x16x32_bf16 v[26:29], v[188:191], v[204:207], v[26:29]
	v_mfma_f32_16x16x32_bf16 v[18:21], v[178:181], v[212:215], v[18:21]
	v_mfma_f32_16x16x32_bf16 v[10:13], v[188:191], v[212:215], v[10:13]
	v_mfma_f32_16x16x32_bf16 v[6:9], v[178:181], v[220:223], v[6:9]
	v_mfma_f32_16x16x32_bf16 v[2:5], v[188:191], v[220:223], v[2:5]
	v_mfma_f32_16x16x32_bf16 v[50:53], v[184:187], v[200:203], v[50:53]
	v_mfma_f32_16x16x32_bf16 v[42:45], v[192:195], v[200:203], v[42:45]
	v_mfma_f32_16x16x32_bf16 v[34:37], v[184:187], v[208:211], v[34:37]
	v_mfma_f32_16x16x32_bf16 v[26:29], v[192:195], v[208:211], v[26:29]
	v_mfma_f32_16x16x32_bf16 v[18:21], v[184:187], v[216:219], v[18:21]
	v_mfma_f32_16x16x32_bf16 v[10:13], v[192:195], v[216:219], v[10:13]
	v_mfma_f32_16x16x32_bf16 v[6:9], v[184:187], v[224:227], v[6:9]
	v_mfma_f32_16x16x32_bf16 v[2:5], v[192:195], v[224:227], v[2:5]
	s_setprio 0
	s_barrier
	s_add_i32 s38, s38, 2
	s_add_u32 s36, s36, 0x100
	s_addc_u32 s37, s37, 0
	s_cmp_gt_u32 s38, 13
	s_mov_b64 s[12:13], s[14:15]

; #define PG8_STAGE(bufoff, gbase, voff) do { _Pragma("unroll") for (int _i = 0; _i < 2; ++_i) \
;         __builtin_amdgcn_global_load_lds((const unsigned*)((const char*)(gbase) + (voff)[_i]), (LAS unsigned*)(lds + (bufoff) + ldsw + _i * 8192), 16, 0, 0); } while (0)
; #define PG8_LDA(dst, b, h) do { _Pragma("unroll") for (int m = 0; m < 4; ++m) _Pragma("unroll") for (int k = 0; k < 2; ++k) dst[m][k] = *(const LAS bf16x8*)(lds + PG8_SA(b, h) + aoff + m * 2048 + k * 1024); } while (0)
; #define PG8_LDB(dst, b, h) do { _Pragma("unroll") for (int n = 0; n < 2; ++n) _Pragma("unroll") for (int k = 0; k < 2; ++k) dst[n][k] = *(const LAS bf16x8*)(lds + PG8_SB(b, h) + boff + n * 2048 + k * 1024); } while (0)
; #define PG8_MMA(ai, bj, At, Bt) do { __builtin_amdgcn_s_setprio(1); _Pragma("unroll") for (int m = 0; m < 4; ++m) _Pragma("unroll") for (int n = 0; n < 2; ++n) _Pragma("unroll") for (int k = 0; k < 2; ++k) \
;         acc[ai][bj][m][n] = __builtin_amdgcn_mfma_f32_16x16x32_bf16(Bt[n][k], At[m][k], acc[ai][bj][m][n], 0, 0, 0); __builtin_amdgcn_s_setprio(0); } while (0)
; #define PG8_WAIT_V(n) asm volatile("s_waitcnt vmcnt(" #n ")" ::: "memory")
; #define PG8_WAIT_L(n) asm volatile("s_waitcnt lgkmcnt(" #n ")" ::: "memory")
; #define PG8_BAR __builtin_amdgcn_s_barrier()
; #define PG8_SCHED __builtin_amdgcn_sched_barrier(0)
; template <class Epi, bool ALIGN_EPI = PG8_ALIGN, bool SP2 = PG8_SP2>
; __device__ __forceinline__ void gemm_phase(LAS uchar* lds, const Gemm g, const StaticOrder& S, const Epi& E) {
;     ...
;             const bool last = (t == nt - 2);
;             const char* a1 = cA + (size_t)(t + 1) * kstep;
;             const char* a2 = last ? nA : cA + (size_t)(t + 2) * kstep; const char* b2 = last ? nB : cB + (size_t)(t + 2) * kstep;
;             const char* a3 = a2 + kstep; const char* b3 = b2 + kstep;
;             if constexpr (SP2) {
;             PG8_LDB(B0, 0, 0); PG8_LDB(B1, 0, 1); PG8_SCHED; PG8_LDA(At, 0, 0); PG8_STAGE(PG8_SA(1, 1), a1 + hstepA, voffA);
;             PG8_WAIT_V(8); PG8_WAIT_L(0); PG8_BAR; PG8_MMA(0, 0, At, B0); PG8_MMA(0, 1, At, B1); PG8_BAR; PG8_SCHED;
.LBB0_1049:
	s_add_u32 s36, s14, 0x100
	s_addc_u32 s37, s15, 0
	s_mov_b32 s38, -2
	s_add_u32 s14, s12, 0x100
	s_addc_u32 s15, s13, 0
	s_add_i32 s39, 0, 0x10000
	s_cmp_eq_u32 s38, 12
	s_cselect_b32 s19, s1, s15
	s_cselect_b32 s18, s0, s14
	v_add_u32_e32 v144, s39, v139
	s_cselect_b32 s17, s11, s37
	s_cselect_b32 s16, s10, s36
	s_add_i32 s40, 0, 0x14000
	ds_read_b128 v[164:167], v144
	ds_read_b128 v[168:171], v144 offset:1024
	ds_read_b128 v[172:175], v144 offset:2048
	ds_read_b128 v[176:179], v144 offset:3072
	v_add_u32_e32 v144, s40, v139
	ds_read_b128 v[184:187], v144
	ds_read_b128 v[188:191], v144 offset:1024
	ds_read_b128 v[192:195], v144 offset:2048
	ds_read_b128 v[196:199], v144 offset:3072
	v_lshl_add_u64 v[160:161], s[12:13], 0, v[156:157]
	s_add_i32 m0, s23, 0xc000
	ds_read_b128 v[200:203], v163
	ds_read_b128 v[204:207], v163 offset:1024
	ds_read_b128 v[208:211], v163 offset:2048
	ds_read_b128 v[212:215], v163 offset:3072
	ds_read_b128 v[216:219], v163 offset:4096
	ds_read_b128 v[220:223], v163 offset:5120
	ds_read_b128 v[224:227], v163 offset:6144
	ds_read_b128 v[228:231], v163 offset:7168
	global_load_lds_dwordx4 v[160:161], off
	v_lshl_add_u64 v[160:161], s[12:13], 0, v[158:159]
	s_add_i32 m0, s23, 0xe000
	s_nop 0
	global_load_lds_dwordx4 v[160:161], off
	s_cmp_lt_i32 s38, 0
	s_cbranch_scc0 .Lrw_std_1050_0_pl
	s_cmp_lt_u32 s29, 2
	s_cbranch_scc1 .Lrw_std_1050_0_pl
	s_waitcnt vmcnt(16)
	s_branch .Lrw_done_1050_0_pl

; #define PG8_STAGE(bufoff, gbase, voff) do { _Pragma("unroll") for (int _i = 0; _i < 2; ++_i) \
;         __builtin_amdgcn_global_load_lds((const unsigned*)((const char*)(gbase) + (voff)[_i]), (LAS unsigned*)(lds + (bufoff) + ldsw + _i * 8192), 16, 0, 0); } while (0)
; #define PG8_LDA(dst, b, h) do { _Pragma("unroll") for (int m = 0; m < 4; ++m) _Pragma("unroll") for (int k = 0; k < 2; ++k) dst[m][k] = *(const LAS bf16x8*)(lds + PG8_SA(b, h) + aoff + m * 2048 + k * 1024); } while (0)
; #define PG8_MMA(ai, bj, At, Bt) do { __builtin_amdgcn_s_setprio(1); _Pragma("unroll") for (int m = 0; m < 4; ++m) _Pragma("unroll") for (int n = 0; n < 2; ++n) _Pragma("unroll") for (int k = 0; k < 2; ++k) \
;         acc[ai][bj][m][n] = __builtin_amdgcn_mfma_f32_16x16x32_bf16(Bt[n][k], At[m][k], acc[ai][bj][m][n], 0, 0, 0); __builtin_amdgcn_s_setprio(0); } while (0)
; #define PG8_WAIT_V(n) asm volatile("s_waitcnt vmcnt(" #n ")" ::: "memory")
; #define PG8_WAIT_L(n) asm volatile("s_waitcnt lgkmcnt(" #n ")" ::: "memory")
; #define PG8_BAR __builtin_amdgcn_s_barrier()
; #define PG8_SCHED __builtin_amdgcn_sched_barrier(0)
; template <class Epi, bool ALIGN_EPI = PG8_ALIGN, bool SP2 = PG8_SP2>
; __device__ __forceinline__ void gemm_phase(LAS uchar* lds, const Gemm g, const StaticOrder& S, const Epi& E) {
;     ...
;             PG8_WAIT_V(8); PG8_WAIT_L(0); PG8_BAR; PG8_MMA(0, 0, At, B0); PG8_MMA(0, 1, At, B1); PG8_BAR; PG8_SCHED;
;             PG8_LDA(At, 0, 1); PG8_STAGE(PG8_SB(0, 0), b2, voffB); PG8_STAGE(PG8_SB(0, 1), b2 + hstepB, voffB); PG8_STAGE(PG8_SA(0, 0), a2, voffA);
;             PG8_WAIT_V(8); PG8_WAIT_L(0); PG8_BAR; PG8_MMA(1, 0, At, B0); PG8_MMA(1, 1, At, B1); PG8_BAR; PG8_SCHED;
.Lrw_done_1050_0_pl:
	s_waitcnt lgkmcnt(0)
	s_barrier
	s_setprio 1
	s_waitcnt lgkmcnt(0)
	v_mfma_f32_16x16x32_bf16 v[126:129], v[164:167], v[200:203], 0
	v_mfma_f32_16x16x32_bf16 v[118:121], v[172:175], v[200:203], 0
	v_mfma_f32_16x16x32_bf16 v[110:113], v[164:167], v[208:211], 0
	v_mfma_f32_16x16x32_bf16 v[102:105], v[172:175], v[208:211], 0
	v_mfma_f32_16x16x32_bf16 v[94:97], v[164:167], v[216:219], 0
	v_mfma_f32_16x16x32_bf16 v[86:89], v[172:175], v[216:219], 0
	v_mfma_f32_16x16x32_bf16 v[78:81], v[164:167], v[224:227], 0
	v_mfma_f32_16x16x32_bf16 v[70:73], v[172:175], v[224:227], 0
	v_mfma_f32_16x16x32_bf16 v[126:129], v[168:171], v[204:207], v[126:129]
	v_mfma_f32_16x16x32_bf16 v[118:121], v[176:179], v[204:207], v[118:121]
	v_mfma_f32_16x16x32_bf16 v[110:113], v[168:171], v[212:215], v[110:113]
	v_mfma_f32_16x16x32_bf16 v[102:105], v[176:179], v[212:215], v[102:105]
	v_mfma_f32_16x16x32_bf16 v[94:97], v[168:171], v[220:223], v[94:97]
	v_mfma_f32_16x16x32_bf16 v[86:89], v[176:179], v[220:223], v[86:89]
	v_mfma_f32_16x16x32_bf16 v[78:81], v[168:171], v[228:231], v[78:81]
	v_mfma_f32_16x16x32_bf16 v[70:73], v[176:179], v[228:231], v[70:73]
	s_setprio 0
	s_setprio 1
	v_mfma_f32_16x16x32_bf16 v[122:125], v[184:187], v[200:203], 0
	v_mfma_f32_16x16x32_bf16 v[114:117], v[192:195], v[200:203], 0
	v_mfma_f32_16x16x32_bf16 v[106:109], v[184:187], v[208:211], 0
	v_mfma_f32_16x16x32_bf16 v[98:101], v[192:195], v[208:211], 0
	v_mfma_f32_16x16x32_bf16 v[90:93], v[184:187], v[216:219], 0
	v_mfma_f32_16x16x32_bf16 v[82:85], v[192:195], v[216:219], 0
	v_mfma_f32_16x16x32_bf16 v[74:77], v[184:187], v[224:227], 0
	v_mfma_f32_16x16x32_bf16 v[66:69], v[192:195], v[224:227], 0
	v_mfma_f32_16x16x32_bf16 v[122:125], v[188:191], v[204:207], v[122:125]
	v_mfma_f32_16x16x32_bf16 v[114:117], v[196:199], v[204:207], v[114:117]
	v_mfma_f32_16x16x32_bf16 v[106:109], v[188:191], v[212:215], v[106:109]
	v_mfma_f32_16x16x32_bf16 v[98:101], v[196:199], v[212:215], v[98:101]
	v_mfma_f32_16x16x32_bf16 v[90:93], v[188:191], v[220:223], v[90:93]
	v_mfma_f32_16x16x32_bf16 v[82:85], v[196:199], v[220:223], v[82:85]
	v_mfma_f32_16x16x32_bf16 v[74:77], v[188:191], v[228:231], v[74:77]
	v_mfma_f32_16x16x32_bf16 v[66:69], v[196:199], v[228:231], v[66:69]
	s_setprio 0
	s_barrier
	s_add_i32 s12, s39, s21
	v_lshl_add_u64 v[160:161], s[16:17], 0, v[134:135]
	s_mov_b32 m0, s12
	ds_read_b128 v[200:203], v163 offset:16384
	ds_read_b128 v[204:207], v163 offset:17408
	ds_read_b128 v[208:211], v163 offset:18432
	ds_read_b128 v[212:215], v163 offset:19456
	ds_read_b128 v[216:219], v163 offset:20480
	ds_read_b128 v[220:223], v163 offset:21504
	ds_read_b128 v[224:227], v163 offset:22528
	ds_read_b128 v[228:231], v163 offset:23552
	global_load_lds_dwordx4 v[160:161], off
	s_add_i32 m0, s12, 0x2000
	s_add_u32 s12, s16, 0x44000
	v_lshl_add_u64 v[180:181], s[16:17], 0, v[130:131]
	s_addc_u32 s13, s17, 0
	s_add_i32 s39, s40, s21
	global_load_lds_dwordx4 v[180:181], off
	v_lshl_add_u64 v[232:233], s[12:13], 0, v[134:135]
	s_mov_b32 m0, s39
	v_lshl_add_u64 v[234:235], s[18:19], 0, v[132:133]
	global_load_lds_dwordx4 v[232:233], off
	v_lshl_add_u64 v[232:233], s[12:13], 0, v[130:131]
	s_add_i32 m0, s39, 0x2000
	s_nop 0
	global_load_lds_dwordx4 v[232:233], off
	v_lshl_add_u64 v[232:233], s[18:19], 0, v[154:155]
	s_mov_b32 m0, s23
	s_nop 0
	global_load_lds_dwordx4 v[232:233], off
	s_mov_b32 m0, s24
	s_nop 0
	global_load_lds_dwordx4 v[234:235], off
	s_cmp_lt_i32 s38, 0
	s_cbranch_scc0 .Lrw_std_1050_1_pl
	s_cmp_lt_u32 s29, 2
	s_cbranch_scc1 .Lrw_std_1050_1_pl
	s_waitcnt vmcnt(16)
	s_branch .Lrw_done_1050_1_pl

; #define PG8_STAGE(bufoff, gbase, voff) do { _Pragma("unroll") for (int _i = 0; _i < 2; ++_i) \
;         __builtin_amdgcn_global_load_lds((const unsigned*)((const char*)(gbase) + (voff)[_i]), (LAS unsigned*)(lds + (bufoff) + ldsw + _i * 8192), 16, 0, 0); } while (0)
; #define PG8_LDA(dst, b, h) do { _Pragma("unroll") for (int m = 0; m < 4; ++m) _Pragma("unroll") for (int k = 0; k < 2; ++k) dst[m][k] = *(const LAS bf16x8*)(lds + PG8_SA(b, h) + aoff + m * 2048 + k * 1024); } while (0)
; #define PG8_LDB(dst, b, h) do { _Pragma("unroll") for (int n = 0; n < 2; ++n) _Pragma("unroll") for (int k = 0; k < 2; ++k) dst[n][k] = *(const LAS bf16x8*)(lds + PG8_SB(b, h) + boff + n * 2048 + k * 1024); } while (0)
; #define PG8_MMA(ai, bj, At, Bt) do { __builtin_amdgcn_s_setprio(1); _Pragma("unroll") for (int m = 0; m < 4; ++m) _Pragma("unroll") for (int n = 0; n < 2; ++n) _Pragma("unroll") for (int k = 0; k < 2; ++k) \
;         acc[ai][bj][m][n] = __builtin_amdgcn_mfma_f32_16x16x32_bf16(Bt[n][k], At[m][k], acc[ai][bj][m][n], 0, 0, 0); __builtin_amdgcn_s_setprio(0); } while (0)
; #define PG8_WAIT_V(n) asm volatile("s_waitcnt vmcnt(" #n ")" ::: "memory")
; #define PG8_WAIT_L(n) asm volatile("s_waitcnt lgkmcnt(" #n ")" ::: "memory")
; #define PG8_BAR __builtin_amdgcn_s_barrier()
; #define PG8_SCHED __builtin_amdgcn_sched_barrier(0)
; template <class Epi, bool ALIGN_EPI = PG8_ALIGN, bool SP2 = PG8_SP2>
; __device__ __forceinline__ void gemm_phase(LAS uchar* lds, const Gemm g, const StaticOrder& S, const Epi& E) {
;     ...
;             PG8_WAIT_V(8); PG8_WAIT_L(0); PG8_BAR; PG8_MMA(1, 0, At, B0); PG8_MMA(1, 1, At, B1); PG8_BAR; PG8_SCHED;
;             PG8_LDB(B0, 1, 0); PG8_LDB(B1, 1, 1); PG8_SCHED; PG8_LDA(At, 1, 0); PG8_STAGE(PG8_SA(0, 1), a2 + hstepA, voffA);
;             PG8_WAIT_V(8); PG8_WAIT_L(0); PG8_BAR; PG8_MMA(0, 0, At, B0); PG8_MMA(0, 1, At, B1); PG8_BAR; PG8_SCHED;
.Lrw_done_1050_1_pl:
	s_waitcnt lgkmcnt(0)
	s_barrier
	s_setprio 1
	s_waitcnt lgkmcnt(0)
	v_mfma_f32_16x16x32_bf16 v[62:65], v[164:167], v[200:203], 0
	v_mfma_f32_16x16x32_bf16 v[54:57], v[172:175], v[200:203], 0
	v_mfma_f32_16x16x32_bf16 v[46:49], v[164:167], v[208:211], 0
	v_mfma_f32_16x16x32_bf16 v[38:41], v[172:175], v[208:211], 0
	v_mfma_f32_16x16x32_bf16 v[30:33], v[164:167], v[216:219], 0
	v_mfma_f32_16x16x32_bf16 v[22:25], v[172:175], v[216:219], 0
	v_mfma_f32_16x16x32_bf16 v[14:17], v[164:167], v[224:227], 0
	v_mfma_f32_16x16x32_bf16 v[6:9], v[172:175], v[224:227], 0
	v_mfma_f32_16x16x32_bf16 v[62:65], v[168:171], v[204:207], v[62:65]
	v_mfma_f32_16x16x32_bf16 v[54:57], v[176:179], v[204:207], v[54:57]
	v_mfma_f32_16x16x32_bf16 v[46:49], v[168:171], v[212:215], v[46:49]
	v_mfma_f32_16x16x32_bf16 v[38:41], v[176:179], v[212:215], v[38:41]
	v_mfma_f32_16x16x32_bf16 v[30:33], v[168:171], v[220:223], v[30:33]
	v_mfma_f32_16x16x32_bf16 v[22:25], v[176:179], v[220:223], v[22:25]
	v_mfma_f32_16x16x32_bf16 v[14:17], v[168:171], v[228:231], v[14:17]
	v_mfma_f32_16x16x32_bf16 v[6:9], v[176:179], v[228:231], v[6:9]
	s_setprio 0
	s_setprio 1
	v_mfma_f32_16x16x32_bf16 v[58:61], v[184:187], v[200:203], 0
	v_mfma_f32_16x16x32_bf16 v[50:53], v[192:195], v[200:203], 0
	v_mfma_f32_16x16x32_bf16 v[42:45], v[184:187], v[208:211], 0
	v_mfma_f32_16x16x32_bf16 v[34:37], v[192:195], v[208:211], 0
	v_mfma_f32_16x16x32_bf16 v[26:29], v[184:187], v[216:219], 0
	v_mfma_f32_16x16x32_bf16 v[18:21], v[192:195], v[216:219], 0
	v_mfma_f32_16x16x32_bf16 v[10:13], v[184:187], v[224:227], 0
	v_mfma_f32_16x16x32_bf16 v[2:5], v[192:195], v[224:227], 0
	v_mfma_f32_16x16x32_bf16 v[58:61], v[188:191], v[204:207], v[58:61]
	v_mfma_f32_16x16x32_bf16 v[50:53], v[196:199], v[204:207], v[50:53]
	v_mfma_f32_16x16x32_bf16 v[42:45], v[188:191], v[212:215], v[42:45]
	v_mfma_f32_16x16x32_bf16 v[34:37], v[196:199], v[212:215], v[34:37]
	v_mfma_f32_16x16x32_bf16 v[26:29], v[188:191], v[220:223], v[26:29]
	v_mfma_f32_16x16x32_bf16 v[18:21], v[196:199], v[220:223], v[18:21]
	v_mfma_f32_16x16x32_bf16 v[10:13], v[188:191], v[228:231], v[10:13]
	v_mfma_f32_16x16x32_bf16 v[2:5], v[196:199], v[228:231], v[2:5]
	s_setprio 0
	s_barrier
	s_add_i32 s39, 0, 0x18000
	v_add_u32_e32 v144, s39, v139
	s_add_i32 s40, 0, 0x1c000
	ds_read_b128 v[164:167], v144
	ds_read_b128 v[168:171], v144 offset:1024
	ds_read_b128 v[172:175], v144 offset:2048
	ds_read_b128 v[176:179], v144 offset:3072
	v_add_u32_e32 v144, s40, v139
	ds_read_b128 v[184:187], v144
	ds_read_b128 v[188:191], v144 offset:1024
	ds_read_b128 v[192:195], v144 offset:2048
	ds_read_b128 v[196:199], v144 offset:3072
	s_add_u32 s12, s18, 0x44000
	s_addc_u32 s13, s19, 0
	s_mov_b32 m0, s25
	v_lshl_add_u64 v[236:237], s[12:13], 0, v[154:155]
	ds_read_b128 v[200:203], v163 offset:32768
	ds_read_b128 v[204:207], v163 offset:33792
	ds_read_b128 v[208:211], v163 offset:34816
	ds_read_b128 v[212:215], v163 offset:35840
	ds_read_b128 v[216:219], v163 offset:36864
	ds_read_b128 v[220:223], v163 offset:37888
	ds_read_b128 v[224:227], v163 offset:38912
	ds_read_b128 v[228:231], v163 offset:39936
	global_load_lds_dwordx4 v[236:237], off
	v_lshl_add_u64 v[236:237], s[12:13], 0, v[132:133]
	s_mov_b32 m0, s26
	s_nop 0
	global_load_lds_dwordx4 v[236:237], off
	s_waitcnt vmcnt(8)
	s_waitcnt lgkmcnt(0)
	s_barrier
	s_setprio 1
	s_waitcnt lgkmcnt(0)
	v_mfma_f32_16x16x32_bf16 v[126:129], v[164:167], v[200:203], v[126:129]
	v_mfma_f32_16x16x32_bf16 v[118:121], v[172:175], v[200:203], v[118:121]
	v_mfma_f32_16x16x32_bf16 v[110:113], v[164:167], v[208:211], v[110:113]
	v_mfma_f32_16x16x32_bf16 v[102:105], v[172:175], v[208:211], v[102:105]
	v_mfma_f32_16x16x32_bf16 v[94:97], v[164:167], v[216:219], v[94:97]
	v_mfma_f32_16x16x32_bf16 v[86:89], v[172:175], v[216:219], v[86:89]
	v_mfma_f32_16x16x32_bf16 v[78:81], v[164:167], v[224:227], v[78:81]
	v_mfma_f32_16x16x32_bf16 v[70:73], v[172:175], v[224:227], v[70:73]
	v_mfma_f32_16x16x32_bf16 v[126:129], v[168:171], v[204:207], v[126:129]
	v_mfma_f32_16x16x32_bf16 v[118:121], v[176:179], v[204:207], v[118:121]
	v_mfma_f32_16x16x32_bf16 v[110:113], v[168:171], v[212:215], v[110:113]
	v_mfma_f32_16x16x32_bf16 v[102:105], v[176:179], v[212:215], v[102:105]
	v_mfma_f32_16x16x32_bf16 v[94:97], v[168:171], v[220:223], v[94:97]
	v_mfma_f32_16x16x32_bf16 v[86:89], v[176:179], v[220:223], v[86:89]
	v_mfma_f32_16x16x32_bf16 v[78:81], v[168:171], v[228:231], v[78:81]
	v_mfma_f32_16x16x32_bf16 v[70:73], v[176:179], v[228:231], v[70:73]
	s_setprio 0
	s_setprio 1
	v_mfma_f32_16x16x32_bf16 v[122:125], v[184:187], v[200:203], v[122:125]
	v_mfma_f32_16x16x32_bf16 v[114:117], v[192:195], v[200:203], v[114:117]
	v_mfma_f32_16x16x32_bf16 v[106:109], v[184:187], v[208:211], v[106:109]
	v_mfma_f32_16x16x32_bf16 v[98:101], v[192:195], v[208:211], v[98:101]
	v_mfma_f32_16x16x32_bf16 v[90:93], v[184:187], v[216:219], v[90:93]
	v_mfma_f32_16x16x32_bf16 v[82:85], v[192:195], v[216:219], v[82:85]
	v_mfma_f32_16x16x32_bf16 v[74:77], v[184:187], v[224:227], v[74:77]
	v_mfma_f32_16x16x32_bf16 v[66:69], v[192:195], v[224:227], v[66:69]
	v_mfma_f32_16x16x32_bf16 v[122:125], v[188:191], v[204:207], v[122:125]
	v_mfma_f32_16x16x32_bf16 v[114:117], v[196:199], v[204:207], v[114:117]
	v_mfma_f32_16x16x32_bf16 v[106:109], v[188:191], v[212:215], v[106:109]
	v_mfma_f32_16x16x32_bf16 v[98:101], v[196:199], v[212:215], v[98:101]
	v_mfma_f32_16x16x32_bf16 v[90:93], v[188:191], v[220:223], v[90:93]
	v_mfma_f32_16x16x32_bf16 v[82:85], v[196:199], v[220:223], v[82:85]
	v_mfma_f32_16x16x32_bf16 v[74:77], v[188:191], v[228:231], v[74:77]
	v_mfma_f32_16x16x32_bf16 v[66:69], v[196:199], v[228:231], v[66:69]
	s_setprio 0
	s_barrier
; #define PG8_STAGE(bufoff, gbase, voff) do { _Pragma("unroll") for (int _i = 0; _i < 2; ++_i) \
;         __builtin_amdgcn_global_load_lds((const unsigned*)((const char*)(gbase) + (voff)[_i]), (LAS unsigned*)(lds + (bufoff) + ldsw + _i * 8192), 16, 0, 0); } while (0)
; #define PG8_LDA(dst, b, h) do { _Pragma("unroll") for (int m = 0; m < 4; ++m) _Pragma("unroll") for (int k = 0; k < 2; ++k) dst[m][k] = *(const LAS bf16x8*)(lds + PG8_SA(b, h) + aoff + m * 2048 + k * 1024); } while (0)
; #define PG8_MMA(ai, bj, At, Bt) do { __builtin_amdgcn_s_setprio(1); _Pragma("unroll") for (int m = 0; m < 4; ++m) _Pragma("unroll") for (int n = 0; n < 2; ++n) _Pragma("unroll") for (int k = 0; k < 2; ++k) \
;         acc[ai][bj][m][n] = __builtin_amdgcn_mfma_f32_16x16x32_bf16(Bt[n][k], At[m][k], acc[ai][bj][m][n], 0, 0, 0); __builtin_amdgcn_s_setprio(0); } while (0)
; #define PG8_WAIT_V(n) asm volatile("s_waitcnt vmcnt(" #n ")" ::: "memory")
; #define PG8_WAIT_L(n) asm volatile("s_waitcnt lgkmcnt(" #n ")" ::: "memory")
; #define PG8_BAR __builtin_amdgcn_s_barrier()
; #define PG8_SCHED __builtin_amdgcn_sched_barrier(0)
; template <class Epi, bool ALIGN_EPI = PG8_ALIGN, bool SP2 = PG8_SP2>
; __device__ __forceinline__ void gemm_phase(LAS uchar* lds, const Gemm g, const StaticOrder& S, const Epi& E) {
;     ...
;             PG8_WAIT_V(8); PG8_WAIT_L(0); PG8_BAR; PG8_MMA(0, 0, At, B0); PG8_MMA(0, 1, At, B1); PG8_BAR; PG8_SCHED;
;             PG8_LDA(At, 1, 1); PG8_STAGE(PG8_SB(1, 0), b3, voffB); PG8_STAGE(PG8_SB(1, 1), b3 + hstepB, voffB); PG8_STAGE(PG8_SA(1, 0), a3, voffA);
;             PG8_WAIT_V(8); PG8_WAIT_L(0); PG8_BAR; PG8_MMA(1, 0, At, B0); PG8_MMA(1, 1, At, B1); PG8_BAR; PG8_SCHED;
	s_add_i32 s12, s39, s21
	v_lshl_add_u64 v[160:161], v[160:161], 0, s[84:85]
	s_mov_b32 m0, s12
	ds_read_b128 v[200:203], v163 offset:49152
	ds_read_b128 v[204:207], v163 offset:50176
	ds_read_b128 v[208:211], v163 offset:51200
	ds_read_b128 v[212:215], v163 offset:52224
	ds_read_b128 v[216:219], v163 offset:53248
	ds_read_b128 v[220:223], v163 offset:54272
	ds_read_b128 v[224:227], v163 offset:55296
	ds_read_b128 v[228:231], v163 offset:56320
	global_load_lds_dwordx4 v[160:161], off
	s_add_i32 m0, s12, 0x2000
	s_add_u32 s12, s16, 0x44080
	v_lshl_add_u64 v[160:161], v[180:181], 0, s[84:85]
	s_addc_u32 s13, s17, 0
	s_add_i32 s16, s40, s21
	global_load_lds_dwordx4 v[160:161], off
	v_lshl_add_u64 v[160:161], s[12:13], 0, v[134:135]
	s_mov_b32 m0, s16
	s_nop 0
	global_load_lds_dwordx4 v[160:161], off
	v_lshl_add_u64 v[160:161], s[12:13], 0, v[130:131]
	s_add_i32 m0, s16, 0x2000
	s_nop 0
	global_load_lds_dwordx4 v[160:161], off
	v_lshl_add_u64 v[160:161], v[232:233], 0, s[84:85]
	s_mov_b32 m0, s27
	s_nop 0
	global_load_lds_dwordx4 v[160:161], off
	v_lshl_add_u64 v[160:161], v[234:235], 0, s[84:85]
	s_mov_b32 m0, s28
	s_nop 0
	global_load_lds_dwordx4 v[160:161], off
	s_waitcnt vmcnt(8)
	s_waitcnt lgkmcnt(0)
	s_barrier
	s_setprio 1
	s_waitcnt lgkmcnt(0)
	v_mfma_f32_16x16x32_bf16 v[62:65], v[164:167], v[200:203], v[62:65]
	v_mfma_f32_16x16x32_bf16 v[54:57], v[172:175], v[200:203], v[54:57]
	v_mfma_f32_16x16x32_bf16 v[46:49], v[164:167], v[208:211], v[46:49]
	v_mfma_f32_16x16x32_bf16 v[38:41], v[172:175], v[208:211], v[38:41]
	v_mfma_f32_16x16x32_bf16 v[30:33], v[164:167], v[216:219], v[30:33]
	v_mfma_f32_16x16x32_bf16 v[22:25], v[172:175], v[216:219], v[22:25]
	v_mfma_f32_16x16x32_bf16 v[14:17], v[164:167], v[224:227], v[14:17]
	v_mfma_f32_16x16x32_bf16 v[6:9], v[172:175], v[224:227], v[6:9]
	v_mfma_f32_16x16x32_bf16 v[62:65], v[168:171], v[204:207], v[62:65]
	v_mfma_f32_16x16x32_bf16 v[54:57], v[176:179], v[204:207], v[54:57]
	v_mfma_f32_16x16x32_bf16 v[46:49], v[168:171], v[212:215], v[46:49]
	v_mfma_f32_16x16x32_bf16 v[38:41], v[176:179], v[212:215], v[38:41]
	v_mfma_f32_16x16x32_bf16 v[30:33], v[168:171], v[220:223], v[30:33]
	v_mfma_f32_16x16x32_bf16 v[22:25], v[176:179], v[220:223], v[22:25]
	v_mfma_f32_16x16x32_bf16 v[14:17], v[168:171], v[228:231], v[14:17]
	v_mfma_f32_16x16x32_bf16 v[6:9], v[176:179], v[228:231], v[6:9]
	s_setprio 0
	s_setprio 1
	v_mfma_f32_16x16x32_bf16 v[58:61], v[184:187], v[200:203], v[58:61]
	v_mfma_f32_16x16x32_bf16 v[50:53], v[192:195], v[200:203], v[50:53]
	v_mfma_f32_16x16x32_bf16 v[42:45], v[184:187], v[208:211], v[42:45]
	v_mfma_f32_16x16x32_bf16 v[34:37], v[192:195], v[208:211], v[34:37]
	v_mfma_f32_16x16x32_bf16 v[26:29], v[184:187], v[216:219], v[26:29]
	v_mfma_f32_16x16x32_bf16 v[18:21], v[192:195], v[216:219], v[18:21]
	v_mfma_f32_16x16x32_bf16 v[10:13], v[184:187], v[224:227], v[10:13]
	v_mfma_f32_16x16x32_bf16 v[2:5], v[192:195], v[224:227], v[2:5]
	v_mfma_f32_16x16x32_bf16 v[58:61], v[188:191], v[204:207], v[58:61]
	v_mfma_f32_16x16x32_bf16 v[50:53], v[196:199], v[204:207], v[50:53]
	v_mfma_f32_16x16x32_bf16 v[42:45], v[188:191], v[212:215], v[42:45]
	v_mfma_f32_16x16x32_bf16 v[34:37], v[196:199], v[212:215], v[34:37]
	v_mfma_f32_16x16x32_bf16 v[26:29], v[188:191], v[220:223], v[26:29]
	v_mfma_f32_16x16x32_bf16 v[18:21], v[196:199], v[220:223], v[18:21]
	v_mfma_f32_16x16x32_bf16 v[10:13], v[188:191], v[228:231], v[10:13]
	v_mfma_f32_16x16x32_bf16 v[2:5], v[196:199], v[228:231], v[2:5]
	s_setprio 0
	s_barrier
	s_add_i32 s38, s38, 2
	s_add_u32 s36, s36, 0x100
	s_addc_u32 s37, s37, 0
	s_cmp_gt_u32 s38, 13
	s_mov_b64 s[12:13], s[14:15]

; #define PG8_STAGE(bufoff, gbase, voff) do { _Pragma("unroll") for (int _i = 0; _i < 2; ++_i) \
;         __builtin_amdgcn_global_load_lds((const unsigned*)((const char*)(gbase) + (voff)[_i]), (LAS unsigned*)(lds + (bufoff) + ldsw + _i * 8192), 16, 0, 0); } while (0)
; #define PG8_LDA(dst, b, h) do { _Pragma("unroll") for (int m = 0; m < 4; ++m) _Pragma("unroll") for (int k = 0; k < 2; ++k) dst[m][k] = *(const LAS bf16x8*)(lds + PG8_SA(b, h) + aoff + m * 2048 + k * 1024); } while (0)
; #define PG8_LDB(dst, b, h) do { _Pragma("unroll") for (int n = 0; n < 2; ++n) _Pragma("unroll") for (int k = 0; k < 2; ++k) dst[n][k] = *(const LAS bf16x8*)(lds + PG8_SB(b, h) + boff + n * 2048 + k * 1024); } while (0)
; #define PG8_MMA(ai, bj, At, Bt) do { __builtin_amdgcn_s_setprio(1); _Pragma("unroll") for (int m = 0; m < 4; ++m) _Pragma("unroll") for (int n = 0; n < 2; ++n) _Pragma("unroll") for (int k = 0; k < 2; ++k) \
;         acc[ai][bj][m][n] = __builtin_amdgcn_mfma_f32_16x16x32_bf16(Bt[n][k], At[m][k], acc[ai][bj][m][n], 0, 0, 0); __builtin_amdgcn_s_setprio(0); } while (0)
; #define PG8_WAIT_V(n) asm volatile("s_waitcnt vmcnt(" #n ")" ::: "memory")
; #define PG8_WAIT_L(n) asm volatile("s_waitcnt lgkmcnt(" #n ")" ::: "memory")
; #define PG8_BAR __builtin_amdgcn_s_barrier()
; #define PG8_SCHED __builtin_amdgcn_sched_barrier(0)
; template <class Epi, bool ALIGN_EPI = PG8_ALIGN, bool SP2 = PG8_SP2>
; __device__ __forceinline__ void gemm_phase(LAS uchar* lds, const Gemm g, const StaticOrder& S, const Epi& E) {
;     ...
;             const bool last = (t == nt - 2);
;             const char* a1 = cA + (size_t)(t + 1) * kstep;
;             const char* a2 = last ? nA : cA + (size_t)(t + 2) * kstep; const char* b2 = last ? nB : cB + (size_t)(t + 2) * kstep;
;             const char* a3 = a2 + kstep; const char* b3 = b2 + kstep;
;             if constexpr (SP2) {
;             PG8_LDB(B0, 0, 0); PG8_LDB(B1, 0, 1); PG8_SCHED; PG8_LDA(At, 0, 0); PG8_STAGE(PG8_SA(1, 1), a1 + hstepA, voffA);
;             PG8_WAIT_V(8); PG8_WAIT_L(0); PG8_BAR; PG8_MMA(0, 0, At, B0); PG8_MMA(0, 1, At, B1); PG8_BAR; PG8_SCHED;
;             PG8_LDA(At, 0, 1); PG8_STAGE(PG8_SB(0, 0), b2, voffB); PG8_STAGE(PG8_SB(0, 1), b2 + hstepB, voffB); PG8_STAGE(PG8_SA(0, 0), a2, voffA);
;             PG8_WAIT_V(8); PG8_WAIT_L(0); PG8_BAR; PG8_MMA(1, 0, At, B0); PG8_MMA(1, 1, At, B1); PG8_BAR; PG8_SCHED;
.LBB0_1142:
	s_add_u32 s38, s16, 0x100
	s_addc_u32 s39, s17, 0
	s_mov_b32 s40, -2
	s_add_u32 s16, s14, 0x100
	s_addc_u32 s17, s15, 0
	s_add_i32 s41, 0, 0x10000
	s_cmp_eq_u32 s40, 40
	s_cselect_b32 s21, s5, s17
	s_cselect_b32 s20, s4, s16
	v_add_u32_e32 v144, s41, v139
	s_cselect_b32 s19, s13, s39
	s_cselect_b32 s18, s12, s38
	s_add_i32 s42, 0, 0x14000
	ds_read_b128 v[160:163], v144
	ds_read_b128 v[166:169], v144 offset:1024
	ds_read_b128 v[170:173], v144 offset:2048
	ds_read_b128 v[174:177], v144 offset:3072
	v_add_u32_e32 v144, s42, v139
	ds_read_b128 v[178:181], v144
	ds_read_b128 v[184:187], v144 offset:1024
	ds_read_b128 v[188:191], v144 offset:2048
	ds_read_b128 v[192:195], v144 offset:3072
	v_lshl_add_u64 v[228:229], s[14:15], 0, v[156:157]
	s_add_i32 m0, s25, 0xc000
	ds_read_b128 v[196:199], v165
	ds_read_b128 v[200:203], v165 offset:1024
	ds_read_b128 v[204:207], v165 offset:2048
	ds_read_b128 v[208:211], v165 offset:3072
	ds_read_b128 v[212:215], v165 offset:4096
	ds_read_b128 v[216:219], v165 offset:5120
	ds_read_b128 v[220:223], v165 offset:6144
	ds_read_b128 v[224:227], v165 offset:7168
	global_load_lds_dwordx4 v[228:229], off
	v_lshl_add_u64 v[228:229], s[14:15], 0, v[158:159]
	s_add_i32 m0, s25, 0xe000
	s_nop 0
	global_load_lds_dwordx4 v[228:229], off
	s_waitcnt vmcnt(8)
	s_waitcnt lgkmcnt(0)
	s_barrier
	s_setprio 1
	s_waitcnt lgkmcnt(0)
	v_mfma_f32_16x16x32_bf16 v[126:129], v[160:163], v[196:199], 0
	v_mfma_f32_16x16x32_bf16 v[122:125], v[170:173], v[196:199], 0
	v_mfma_f32_16x16x32_bf16 v[118:121], v[160:163], v[204:207], 0
	v_mfma_f32_16x16x32_bf16 v[110:113], v[170:173], v[204:207], 0
	v_mfma_f32_16x16x32_bf16 v[102:105], v[160:163], v[212:215], 0
	v_mfma_f32_16x16x32_bf16 v[94:97], v[170:173], v[212:215], 0
	v_mfma_f32_16x16x32_bf16 v[86:89], v[160:163], v[220:223], 0
	v_mfma_f32_16x16x32_bf16 v[78:81], v[170:173], v[220:223], 0
	v_mfma_f32_16x16x32_bf16 v[126:129], v[166:169], v[200:203], v[126:129]
	v_mfma_f32_16x16x32_bf16 v[122:125], v[174:177], v[200:203], v[122:125]
	v_mfma_f32_16x16x32_bf16 v[118:121], v[166:169], v[208:211], v[118:121]
	v_mfma_f32_16x16x32_bf16 v[110:113], v[174:177], v[208:211], v[110:113]
	v_mfma_f32_16x16x32_bf16 v[102:105], v[166:169], v[216:219], v[102:105]
	v_mfma_f32_16x16x32_bf16 v[94:97], v[174:177], v[216:219], v[94:97]
	v_mfma_f32_16x16x32_bf16 v[86:89], v[166:169], v[224:227], v[86:89]
	v_mfma_f32_16x16x32_bf16 v[78:81], v[174:177], v[224:227], v[78:81]
	s_setprio 0
	s_setprio 1
	v_mfma_f32_16x16x32_bf16 v[114:117], v[178:181], v[196:199], 0
	v_mfma_f32_16x16x32_bf16 v[106:109], v[188:191], v[196:199], 0
	v_mfma_f32_16x16x32_bf16 v[98:101], v[178:181], v[204:207], 0
	v_mfma_f32_16x16x32_bf16 v[90:93], v[188:191], v[204:207], 0
	v_mfma_f32_16x16x32_bf16 v[82:85], v[178:181], v[212:215], 0
	v_mfma_f32_16x16x32_bf16 v[74:77], v[188:191], v[212:215], 0
	v_mfma_f32_16x16x32_bf16 v[70:73], v[178:181], v[220:223], 0
	v_mfma_f32_16x16x32_bf16 v[66:69], v[188:191], v[220:223], 0
	v_mfma_f32_16x16x32_bf16 v[114:117], v[184:187], v[200:203], v[114:117]
	v_mfma_f32_16x16x32_bf16 v[106:109], v[192:195], v[200:203], v[106:109]
	v_mfma_f32_16x16x32_bf16 v[98:101], v[184:187], v[208:211], v[98:101]
	v_mfma_f32_16x16x32_bf16 v[90:93], v[192:195], v[208:211], v[90:93]
	v_mfma_f32_16x16x32_bf16 v[82:85], v[184:187], v[216:219], v[82:85]
	v_mfma_f32_16x16x32_bf16 v[74:77], v[192:195], v[216:219], v[74:77]
	v_mfma_f32_16x16x32_bf16 v[70:73], v[184:187], v[224:227], v[70:73]
	v_mfma_f32_16x16x32_bf16 v[66:69], v[192:195], v[224:227], v[66:69]
	s_setprio 0
	s_barrier
	s_add_i32 s14, s41, s24
	v_lshl_add_u64 v[228:229], s[18:19], 0, v[132:133]
	s_mov_b32 m0, s14
	ds_read_b128 v[196:199], v165 offset:16384
	ds_read_b128 v[200:203], v165 offset:17408
	ds_read_b128 v[204:207], v165 offset:18432
	ds_read_b128 v[208:211], v165 offset:19456
	ds_read_b128 v[212:215], v165 offset:20480
	ds_read_b128 v[216:219], v165 offset:21504
	ds_read_b128 v[220:223], v165 offset:22528
	ds_read_b128 v[224:227], v165 offset:23552
	global_load_lds_dwordx4 v[228:229], off
	s_add_i32 m0, s14, 0x2000
	s_add_u32 s14, s18, 0xb0000
	v_lshl_add_u64 v[230:231], s[18:19], 0, v[154:155]
	s_addc_u32 s15, s19, 0
	s_add_i32 s41, s42, s24
	global_load_lds_dwordx4 v[230:231], off
	v_lshl_add_u64 v[232:233], s[14:15], 0, v[132:133]
	s_mov_b32 m0, s41
	v_lshl_add_u64 v[234:235], s[20:21], 0, v[134:135]
	global_load_lds_dwordx4 v[232:233], off
	v_lshl_add_u64 v[232:233], s[14:15], 0, v[154:155]
	s_add_i32 m0, s41, 0x2000
	s_nop 0
	global_load_lds_dwordx4 v[232:233], off
	v_lshl_add_u64 v[232:233], s[20:21], 0, v[130:131]
	s_mov_b32 m0, s25
	s_nop 0
	global_load_lds_dwordx4 v[232:233], off
	s_mov_b32 m0, s26
	s_nop 0
	global_load_lds_dwordx4 v[234:235], off
	s_waitcnt vmcnt(8)
	s_waitcnt lgkmcnt(0)
	s_barrier
; #define PG8_STAGE(bufoff, gbase, voff) do { _Pragma("unroll") for (int _i = 0; _i < 2; ++_i) \
;         __builtin_amdgcn_global_load_lds((const unsigned*)((const char*)(gbase) + (voff)[_i]), (LAS unsigned*)(lds + (bufoff) + ldsw + _i * 8192), 16, 0, 0); } while (0)
; #define PG8_LDA(dst, b, h) do { _Pragma("unroll") for (int m = 0; m < 4; ++m) _Pragma("unroll") for (int k = 0; k < 2; ++k) dst[m][k] = *(const LAS bf16x8*)(lds + PG8_SA(b, h) + aoff + m * 2048 + k * 1024); } while (0)
; #define PG8_LDB(dst, b, h) do { _Pragma("unroll") for (int n = 0; n < 2; ++n) _Pragma("unroll") for (int k = 0; k < 2; ++k) dst[n][k] = *(const LAS bf16x8*)(lds + PG8_SB(b, h) + boff + n * 2048 + k * 1024); } while (0)
; #define PG8_MMA(ai, bj, At, Bt) do { __builtin_amdgcn_s_setprio(1); _Pragma("unroll") for (int m = 0; m < 4; ++m) _Pragma("unroll") for (int n = 0; n < 2; ++n) _Pragma("unroll") for (int k = 0; k < 2; ++k) \
;         acc[ai][bj][m][n] = __builtin_amdgcn_mfma_f32_16x16x32_bf16(Bt[n][k], At[m][k], acc[ai][bj][m][n], 0, 0, 0); __builtin_amdgcn_s_setprio(0); } while (0)
; #define PG8_WAIT_V(n) asm volatile("s_waitcnt vmcnt(" #n ")" ::: "memory")
; #define PG8_WAIT_L(n) asm volatile("s_waitcnt lgkmcnt(" #n ")" ::: "memory")
; #define PG8_BAR __builtin_amdgcn_s_barrier()
; #define PG8_SCHED __builtin_amdgcn_sched_barrier(0)
; template <class Epi, bool ALIGN_EPI = PG8_ALIGN, bool SP2 = PG8_SP2>
; __device__ __forceinline__ void gemm_phase(LAS uchar* lds, const Gemm g, const StaticOrder& S, const Epi& E) {
;     ...
;             PG8_WAIT_V(8); PG8_WAIT_L(0); PG8_BAR; PG8_MMA(1, 0, At, B0); PG8_MMA(1, 1, At, B1); PG8_BAR; PG8_SCHED;
;             PG8_LDB(B0, 1, 0); PG8_LDB(B1, 1, 1); PG8_SCHED; PG8_LDA(At, 1, 0); PG8_STAGE(PG8_SA(0, 1), a2 + hstepA, voffA);
;             PG8_WAIT_V(8); PG8_WAIT_L(0); PG8_BAR; PG8_MMA(0, 0, At, B0); PG8_MMA(0, 1, At, B1); PG8_BAR; PG8_SCHED;
	s_setprio 1
	s_waitcnt lgkmcnt(0)
	v_mfma_f32_16x16x32_bf16 v[62:65], v[160:163], v[196:199], 0
	v_mfma_f32_16x16x32_bf16 v[58:61], v[170:173], v[196:199], 0
	v_mfma_f32_16x16x32_bf16 v[54:57], v[160:163], v[204:207], 0
	v_mfma_f32_16x16x32_bf16 v[46:49], v[170:173], v[204:207], 0
	v_mfma_f32_16x16x32_bf16 v[38:41], v[160:163], v[212:215], 0
	v_mfma_f32_16x16x32_bf16 v[30:33], v[170:173], v[212:215], 0
	v_mfma_f32_16x16x32_bf16 v[22:25], v[160:163], v[220:223], 0
	v_mfma_f32_16x16x32_bf16 v[14:17], v[170:173], v[220:223], 0
	v_mfma_f32_16x16x32_bf16 v[62:65], v[166:169], v[200:203], v[62:65]
	v_mfma_f32_16x16x32_bf16 v[58:61], v[174:177], v[200:203], v[58:61]
	v_mfma_f32_16x16x32_bf16 v[54:57], v[166:169], v[208:211], v[54:57]
	v_mfma_f32_16x16x32_bf16 v[46:49], v[174:177], v[208:211], v[46:49]
	v_mfma_f32_16x16x32_bf16 v[38:41], v[166:169], v[216:219], v[38:41]
	v_mfma_f32_16x16x32_bf16 v[30:33], v[174:177], v[216:219], v[30:33]
	v_mfma_f32_16x16x32_bf16 v[22:25], v[166:169], v[224:227], v[22:25]
	v_mfma_f32_16x16x32_bf16 v[14:17], v[174:177], v[224:227], v[14:17]
	s_setprio 0
	s_setprio 1
	v_mfma_f32_16x16x32_bf16 v[50:53], v[178:181], v[196:199], 0
	v_mfma_f32_16x16x32_bf16 v[42:45], v[188:191], v[196:199], 0
	v_mfma_f32_16x16x32_bf16 v[34:37], v[178:181], v[204:207], 0
	v_mfma_f32_16x16x32_bf16 v[26:29], v[188:191], v[204:207], 0
	v_mfma_f32_16x16x32_bf16 v[18:21], v[178:181], v[212:215], 0
	v_mfma_f32_16x16x32_bf16 v[10:13], v[188:191], v[212:215], 0
	v_mfma_f32_16x16x32_bf16 v[6:9], v[178:181], v[220:223], 0
	v_mfma_f32_16x16x32_bf16 v[2:5], v[188:191], v[220:223], 0
	v_mfma_f32_16x16x32_bf16 v[50:53], v[184:187], v[200:203], v[50:53]
	v_mfma_f32_16x16x32_bf16 v[42:45], v[192:195], v[200:203], v[42:45]
	v_mfma_f32_16x16x32_bf16 v[34:37], v[184:187], v[208:211], v[34:37]
	v_mfma_f32_16x16x32_bf16 v[26:29], v[192:195], v[208:211], v[26:29]
	v_mfma_f32_16x16x32_bf16 v[18:21], v[184:187], v[216:219], v[18:21]
	v_mfma_f32_16x16x32_bf16 v[10:13], v[192:195], v[216:219], v[10:13]
	v_mfma_f32_16x16x32_bf16 v[6:9], v[184:187], v[224:227], v[6:9]
	v_mfma_f32_16x16x32_bf16 v[2:5], v[192:195], v[224:227], v[2:5]
	s_setprio 0
	s_barrier
	s_add_i32 s41, 0, 0x18000
	v_add_u32_e32 v144, s41, v139
	s_add_i32 s42, 0, 0x1c000
	ds_read_b128 v[160:163], v144
	ds_read_b128 v[166:169], v144 offset:1024
	ds_read_b128 v[170:173], v144 offset:2048
	ds_read_b128 v[174:177], v144 offset:3072
	v_add_u32_e32 v144, s42, v139
	ds_read_b128 v[178:181], v144
	ds_read_b128 v[184:187], v144 offset:1024
	ds_read_b128 v[188:191], v144 offset:2048
	ds_read_b128 v[192:195], v144 offset:3072
	s_add_u32 s14, s20, 0xb0000
	s_addc_u32 s15, s21, 0
	s_mov_b32 m0, s27
	v_lshl_add_u64 v[236:237], s[14:15], 0, v[130:131]
	ds_read_b128 v[196:199], v165 offset:32768
	ds_read_b128 v[200:203], v165 offset:33792
	ds_read_b128 v[204:207], v165 offset:34816
	ds_read_b128 v[208:211], v165 offset:35840
	ds_read_b128 v[212:215], v165 offset:36864
	ds_read_b128 v[216:219], v165 offset:37888
	ds_read_b128 v[220:223], v165 offset:38912
	ds_read_b128 v[224:227], v165 offset:39936
	global_load_lds_dwordx4 v[236:237], off
	v_lshl_add_u64 v[236:237], s[14:15], 0, v[134:135]
	s_mov_b32 m0, s28
	s_nop 0
	global_load_lds_dwordx4 v[236:237], off
	s_waitcnt vmcnt(8)
	s_waitcnt lgkmcnt(0)
	s_barrier
	s_setprio 1
	s_waitcnt lgkmcnt(0)
	v_mfma_f32_16x16x32_bf16 v[126:129], v[160:163], v[196:199], v[126:129]
	v_mfma_f32_16x16x32_bf16 v[122:125], v[170:173], v[196:199], v[122:125]
	v_mfma_f32_16x16x32_bf16 v[118:121], v[160:163], v[204:207], v[118:121]
	v_mfma_f32_16x16x32_bf16 v[110:113], v[170:173], v[204:207], v[110:113]
	v_mfma_f32_16x16x32_bf16 v[102:105], v[160:163], v[212:215], v[102:105]
	v_mfma_f32_16x16x32_bf16 v[94:97], v[170:173], v[212:215], v[94:97]
	v_mfma_f32_16x16x32_bf16 v[86:89], v[160:163], v[220:223], v[86:89]
	v_mfma_f32_16x16x32_bf16 v[78:81], v[170:173], v[220:223], v[78:81]
	v_mfma_f32_16x16x32_bf16 v[126:129], v[166:169], v[200:203], v[126:129]
	v_mfma_f32_16x16x32_bf16 v[122:125], v[174:177], v[200:203], v[122:125]
	v_mfma_f32_16x16x32_bf16 v[118:121], v[166:169], v[208:211], v[118:121]
	v_mfma_f32_16x16x32_bf16 v[110:113], v[174:177], v[208:211], v[110:113]
	v_mfma_f32_16x16x32_bf16 v[102:105], v[166:169], v[216:219], v[102:105]
	v_mfma_f32_16x16x32_bf16 v[94:97], v[174:177], v[216:219], v[94:97]
	v_mfma_f32_16x16x32_bf16 v[86:89], v[166:169], v[224:227], v[86:89]
	v_mfma_f32_16x16x32_bf16 v[78:81], v[174:177], v[224:227], v[78:81]
	s_setprio 0
	s_setprio 1
	v_mfma_f32_16x16x32_bf16 v[114:117], v[178:181], v[196:199], v[114:117]
	v_mfma_f32_16x16x32_bf16 v[106:109], v[188:191], v[196:199], v[106:109]
	v_mfma_f32_16x16x32_bf16 v[98:101], v[178:181], v[204:207], v[98:101]
	v_mfma_f32_16x16x32_bf16 v[90:93], v[188:191], v[204:207], v[90:93]
	v_mfma_f32_16x16x32_bf16 v[82:85], v[178:181], v[212:215], v[82:85]
	v_mfma_f32_16x16x32_bf16 v[74:77], v[188:191], v[212:215], v[74:77]
	v_mfma_f32_16x16x32_bf16 v[70:73], v[178:181], v[220:223], v[70:73]
	v_mfma_f32_16x16x32_bf16 v[66:69], v[188:191], v[220:223], v[66:69]
	v_mfma_f32_16x16x32_bf16 v[114:117], v[184:187], v[200:203], v[114:117]
	v_mfma_f32_16x16x32_bf16 v[106:109], v[192:195], v[200:203], v[106:109]
	v_mfma_f32_16x16x32_bf16 v[98:101], v[184:187], v[208:211], v[98:101]
	v_mfma_f32_16x16x32_bf16 v[90:93], v[192:195], v[208:211], v[90:93]
	v_mfma_f32_16x16x32_bf16 v[82:85], v[184:187], v[216:219], v[82:85]
	v_mfma_f32_16x16x32_bf16 v[74:77], v[192:195], v[216:219], v[74:77]
	v_mfma_f32_16x16x32_bf16 v[70:73], v[184:187], v[224:227], v[70:73]
	v_mfma_f32_16x16x32_bf16 v[66:69], v[192:195], v[224:227], v[66:69]
	s_setprio 0
	s_barrier
; #define PG8_STAGE(bufoff, gbase, voff) do { _Pragma("unroll") for (int _i = 0; _i < 2; ++_i) \
;         __builtin_amdgcn_global_load_lds((const unsigned*)((const char*)(gbase) + (voff)[_i]), (LAS unsigned*)(lds + (bufoff) + ldsw + _i * 8192), 16, 0, 0); } while (0)
; #define PG8_LDA(dst, b, h) do { _Pragma("unroll") for (int m = 0; m < 4; ++m) _Pragma("unroll") for (int k = 0; k < 2; ++k) dst[m][k] = *(const LAS bf16x8*)(lds + PG8_SA(b, h) + aoff + m * 2048 + k * 1024); } while (0)
; #define PG8_MMA(ai, bj, At, Bt) do { __builtin_amdgcn_s_setprio(1); _Pragma("unroll") for (int m = 0; m < 4; ++m) _Pragma("unroll") for (int n = 0; n < 2; ++n) _Pragma("unroll") for (int k = 0; k < 2; ++k) \
;         acc[ai][bj][m][n] = __builtin_amdgcn_mfma_f32_16x16x32_bf16(Bt[n][k], At[m][k], acc[ai][bj][m][n], 0, 0, 0); __builtin_amdgcn_s_setprio(0); } while (0)
; #define PG8_WAIT_V(n) asm volatile("s_waitcnt vmcnt(" #n ")" ::: "memory")
; #define PG8_WAIT_L(n) asm volatile("s_waitcnt lgkmcnt(" #n ")" ::: "memory")
; #define PG8_BAR __builtin_amdgcn_s_barrier()
; #define PG8_SCHED __builtin_amdgcn_sched_barrier(0)
; template <class Epi, bool ALIGN_EPI = PG8_ALIGN, bool SP2 = PG8_SP2>
; __device__ __forceinline__ void gemm_phase(LAS uchar* lds, const Gemm g, const StaticOrder& S, const Epi& E) {
;     ...
;             PG8_WAIT_V(8); PG8_WAIT_L(0); PG8_BAR; PG8_MMA(0, 0, At, B0); PG8_MMA(0, 1, At, B1); PG8_BAR; PG8_SCHED;
;             PG8_LDA(At, 1, 1); PG8_STAGE(PG8_SB(1, 0), b3, voffB); PG8_STAGE(PG8_SB(1, 1), b3 + hstepB, voffB); PG8_STAGE(PG8_SA(1, 0), a3, voffA);
;             PG8_WAIT_V(8); PG8_WAIT_L(0); PG8_BAR; PG8_MMA(1, 0, At, B0); PG8_MMA(1, 1, At, B1); PG8_BAR; PG8_SCHED;
	s_add_i32 s14, s41, s24
	v_lshl_add_u64 v[228:229], v[228:229], 0, s[84:85]
	s_mov_b32 m0, s14
	ds_read_b128 v[196:199], v165 offset:49152
	ds_read_b128 v[200:203], v165 offset:50176
	ds_read_b128 v[204:207], v165 offset:51200
	ds_read_b128 v[208:211], v165 offset:52224
	ds_read_b128 v[212:215], v165 offset:53248
	ds_read_b128 v[216:219], v165 offset:54272
	ds_read_b128 v[220:223], v165 offset:55296
	ds_read_b128 v[224:227], v165 offset:56320
	global_load_lds_dwordx4 v[228:229], off
	s_add_i32 m0, s14, 0x2000
	s_add_u32 s14, s18, 0xb0080
	v_lshl_add_u64 v[228:229], v[230:231], 0, s[84:85]
	s_addc_u32 s15, s19, 0
	s_add_i32 s18, s42, s24
	global_load_lds_dwordx4 v[228:229], off
	v_lshl_add_u64 v[228:229], s[14:15], 0, v[132:133]
	s_mov_b32 m0, s18
	s_nop 0
	global_load_lds_dwordx4 v[228:229], off
	v_lshl_add_u64 v[228:229], s[14:15], 0, v[154:155]
	s_add_i32 m0, s18, 0x2000
	s_nop 0
	global_load_lds_dwordx4 v[228:229], off
	v_lshl_add_u64 v[228:229], v[232:233], 0, s[84:85]
	s_mov_b32 m0, s29
	s_nop 0
	global_load_lds_dwordx4 v[228:229], off
	v_lshl_add_u64 v[228:229], v[234:235], 0, s[84:85]
	s_mov_b32 m0, s30
	s_nop 0
	global_load_lds_dwordx4 v[228:229], off
	s_waitcnt vmcnt(8)
	s_waitcnt lgkmcnt(0)
	s_barrier
	s_setprio 1
	s_waitcnt lgkmcnt(0)
	v_mfma_f32_16x16x32_bf16 v[62:65], v[160:163], v[196:199], v[62:65]
	v_mfma_f32_16x16x32_bf16 v[58:61], v[170:173], v[196:199], v[58:61]
	v_mfma_f32_16x16x32_bf16 v[54:57], v[160:163], v[204:207], v[54:57]
	v_mfma_f32_16x16x32_bf16 v[46:49], v[170:173], v[204:207], v[46:49]
	v_mfma_f32_16x16x32_bf16 v[38:41], v[160:163], v[212:215], v[38:41]
	v_mfma_f32_16x16x32_bf16 v[30:33], v[170:173], v[212:215], v[30:33]
	v_mfma_f32_16x16x32_bf16 v[22:25], v[160:163], v[220:223], v[22:25]
	v_mfma_f32_16x16x32_bf16 v[14:17], v[170:173], v[220:223], v[14:17]
	v_mfma_f32_16x16x32_bf16 v[62:65], v[166:169], v[200:203], v[62:65]
	v_mfma_f32_16x16x32_bf16 v[58:61], v[174:177], v[200:203], v[58:61]
	v_mfma_f32_16x16x32_bf16 v[54:57], v[166:169], v[208:211], v[54:57]
	v_mfma_f32_16x16x32_bf16 v[46:49], v[174:177], v[208:211], v[46:49]
	v_mfma_f32_16x16x32_bf16 v[38:41], v[166:169], v[216:219], v[38:41]
	v_mfma_f32_16x16x32_bf16 v[30:33], v[174:177], v[216:219], v[30:33]
	v_mfma_f32_16x16x32_bf16 v[22:25], v[166:169], v[224:227], v[22:25]
	v_mfma_f32_16x16x32_bf16 v[14:17], v[174:177], v[224:227], v[14:17]
	s_setprio 0
	s_setprio 1
	v_mfma_f32_16x16x32_bf16 v[50:53], v[178:181], v[196:199], v[50:53]
	v_mfma_f32_16x16x32_bf16 v[42:45], v[188:191], v[196:199], v[42:45]
	v_mfma_f32_16x16x32_bf16 v[34:37], v[178:181], v[204:207], v[34:37]
	v_mfma_f32_16x16x32_bf16 v[26:29], v[188:191], v[204:207], v[26:29]
	v_mfma_f32_16x16x32_bf16 v[18:21], v[178:181], v[212:215], v[18:21]
	v_mfma_f32_16x16x32_bf16 v[10:13], v[188:191], v[212:215], v[10:13]
	v_mfma_f32_16x16x32_bf16 v[6:9], v[178:181], v[220:223], v[6:9]
	v_mfma_f32_16x16x32_bf16 v[2:5], v[188:191], v[220:223], v[2:5]
	v_mfma_f32_16x16x32_bf16 v[50:53], v[184:187], v[200:203], v[50:53]
	v_mfma_f32_16x16x32_bf16 v[42:45], v[192:195], v[200:203], v[42:45]
	v_mfma_f32_16x16x32_bf16 v[34:37], v[184:187], v[208:211], v[34:37]
	v_mfma_f32_16x16x32_bf16 v[26:29], v[192:195], v[208:211], v[26:29]
	v_mfma_f32_16x16x32_bf16 v[18:21], v[184:187], v[216:219], v[18:21]
	v_mfma_f32_16x16x32_bf16 v[10:13], v[192:195], v[216:219], v[10:13]
	v_mfma_f32_16x16x32_bf16 v[6:9], v[184:187], v[224:227], v[6:9]
	v_mfma_f32_16x16x32_bf16 v[2:5], v[192:195], v[224:227], v[2:5]
	s_setprio 0
	s_barrier
	s_add_i32 s40, s40, 2
	s_add_u32 s38, s38, 0x100
	s_addc_u32 s39, s39, 0
	s_cmp_gt_u32 s40, 41
	s_mov_b64 s[14:15], s[16:17]
